# GEMM loops (all but hgin): staged-load addresses kept in persistent VGPR pairs so each half issues its 8 loads back to back
# baseline (speedup 1.0000x reference)
; DEV int tidx() { int t = threadIdx.x; asm volatile("" : "+v"(t)); return t; }
; #define G_LOAD(RA, RB, KT) { _Pragma("unroll") for (int i = 0; i < 4; i++) { \
;       RA[i] = *(const u32x4*)(Ap + (size_t)(i * 32) * lda + (KT) * 64); RB[i] = *(const u32x4*)(Bp + (size_t)(i * 32) * ldb + (KT) * 64); } }
; template <class Epi>
; DEV void gemm_tile(const bf16_t* __restrict__ A, int lda, const bf16_t* __restrict__ Bt, int ldb, int K, int m0, int n0,
;                    Epi& epi, char* smem) {
;   bf16_t* As = (bf16_t*)smem;
;   bf16_t* Bs = As + 128 * GLD;
;   const int tid = tidx(), lane = tid & 63, w = tid >> 6, wm = w >> 1, wn = w & 1;
;   const int l15 = lane & 15, quad = lane >> 4;
;   f32x4 acc[4][4];
; #pragma unroll
;   for (int i = 0; i < 4; i++)
; #pragma unroll
;     for (int j = 0; j < 4; j++) acc[i][j] = (f32x4){0.f, 0.f, 0.f, 0.f};
;   u32x4 ra0[4], rb0[4], ra1[4], rb1[4];
;   const int nk = K >> 6;
;   const int lrow = tid >> 3, lcc = tid & 7;
;   const bf16_t* Ap = A + (size_t)(m0 + lrow) * lda + lcc * 8;
;   const bf16_t* Bp = Bt + (size_t)(n0 + lrow) * ldb + lcc * 8;
;     ...
;   G_LOAD(ra0, rb0, 0);
;   G_LOAD(ra1, rb1, 1);
.LBB0_179:
	s_ashr_i32 s13, s1, 6
	s_and_b32 s2, s1, 7
	s_and_b32 s3, s13, -8
	s_or_b32 s2, s3, s2
	s_lshr_b32 s3, s1, 31
	s_add_i32 s3, s2, s3
	s_ashr_i32 s12, s3, 1
	s_lshl_b32 s3, s12, 3
	s_bfe_u32 s14, s1, 0x30006
	s_or_b32 s3, s3, s14
	s_cmpk_gt_i32 s3, 0x7f
	s_cbranch_scc1 .LBB0_178
	v_mov_b32_e32 v145, v195
	s_lshr_b32 s14, s1, 6
	s_lshl_b32 s2, s2, 3
	s_lshl_b32 s18, s12, 4
	s_lshl_b32 s3, s3, 7
	s_and_b32 s15, s0, 7
	v_ashrrev_i32_e32 v66, 3, v145
	s_and_b32 s14, s14, 7
	s_sub_i32 s2, s2, s18
	s_movk_i32 s20, 0x880
	s_bfe_u32 s19, s1, 0x30003
	v_add_u32_e32 v0, s3, v66
	v_mov_b64_e32 v[2:3], s[10:11]
	s_lshl_b32 s16, s15, 3
	s_lshl_b32 s17, s14, 7
	s_or_b32 s2, s2, s19
	v_mad_i64_i32 v[2:3], s[14:15], v0, s20, v[2:3]
	v_lshlrev_b32_e32 v0, 4, v145
	s_lshl_b32 s2, s2, 7
	v_and_b32_e32 v0, 0x70, v0
	v_lshl_add_u64 v[6:7], v[2:3], 0, v[0:1]
	v_add_u32_e32 v4, s2, v66
	v_mov_b64_e32 v[2:3], s[8:9]
	v_mad_i64_i32 v[2:3], s[14:15], v4, s20, v[2:3]
	s_mov_b32 s14, 0x11000
	s_waitcnt vmcnt(21)
	v_add_co_u32_e32 v22, vcc, s14, v6
	v_lshl_add_u64 v[14:15], v[2:3], 0, v[0:1]
	s_nop 0
	v_addc_co_u32_e32 v23, vcc, 0, v7, vcc
	s_waitcnt vmcnt(20)
	v_add_co_u32_e32 v30, vcc, s14, v14
	s_mov_b32 s14, 0x22000
	s_nop 0
	v_addc_co_u32_e32 v31, vcc, 0, v15, vcc
	s_waitcnt vmcnt(19)
	v_add_co_u32_e32 v38, vcc, s14, v6
	s_lshl_b32 s13, s13, 3
	s_nop 0
	v_addc_co_u32_e32 v39, vcc, 0, v7, vcc
	s_waitcnt vmcnt(18)
	v_add_co_u32_e32 v46, vcc, s14, v14
	s_mov_b32 s14, 0x33000
	s_nop 0
	v_addc_co_u32_e32 v47, vcc, 0, v15, vcc
	s_waitcnt vmcnt(17)
	v_add_co_u32_e32 v54, vcc, s14, v6
	s_and_b32 s13, s13, 0x1ffffc0
	s_nop 0
	v_addc_co_u32_e32 v55, vcc, 0, v7, vcc
	s_waitcnt vmcnt(16)
	v_add_co_u32_e32 v62, vcc, s14, v14
	s_or_b32 s13, s13, s16
	s_nop 0
	v_addc_co_u32_e32 v63, vcc, 0, v15, vcc
	global_load_dwordx4 v[2:5], v[6:7], off
	s_nop 0
	global_load_dwordx4 v[10:13], v[14:15], off
	s_nop 0
	global_load_dwordx4 v[18:21], v[22:23], off
	s_nop 0
	global_load_dwordx4 v[26:29], v[30:31], off
	s_nop 0
	global_load_dwordx4 v[34:37], v[38:39], off
	s_nop 0
	global_load_dwordx4 v[42:45], v[46:47], off
	s_nop 0
	global_load_dwordx4 v[50:53], v[54:55], off
	s_nop 0
	global_load_dwordx4 v[58:61], v[62:63], off
	s_nop 0
	v_mov_b64_e32 v[188:189], v[6:7]
	v_mov_b64_e32 v[190:191], v[14:15]
	v_mov_b64_e32 v[192:193], v[22:23]
	v_mov_b64_e32 v[236:237], v[30:31]
	v_mov_b64_e32 v[240:241], v[38:39]
	v_mov_b64_e32 v[242:243], v[46:47]
	v_mov_b64_e32 v[244:245], v[54:55]
	v_mov_b64_e32 v[246:247], v[62:63]
	global_load_dwordx4 v[6:9], v[6:7], off offset:128
	s_nop 0
	global_load_dwordx4 v[14:17], v[14:15], off offset:128
	s_nop 0
	global_load_dwordx4 v[22:25], v[22:23], off offset:128
	s_nop 0
	global_load_dwordx4 v[30:33], v[30:31], off offset:128
	s_nop 0
	global_load_dwordx4 v[38:41], v[38:39], off offset:128
	s_nop 0
	global_load_dwordx4 v[46:49], v[46:47], off offset:128
	s_nop 0
	global_load_dwordx4 v[54:57], v[54:55], off offset:128
	s_nop 0
	global_load_dwordx4 v[62:65], v[62:63], off offset:128
	s_or_b32 s13, s13, s19
	v_mad_u64_u32 v[134:135], s[14:15], v66, s36, v[0:1]
	s_sub_i32 s13, s13, s18
	v_ashrrev_i32_e32 v67, 1, v145
	s_lshl_b32 s14, s13, 7
	s_lshl_b32 s12, s12, 10
	v_and_b32_e32 v146, 0xffffffc0, v67
	v_ashrrev_i32_e32 v67, 31, v66
	s_ashr_i32 s15, s14, 31
	s_or_b32 s12, s17, s12
	s_movk_i32 s19, 0x880
	v_lshl_add_u64 v[68:69], v[66:67], 0, s[14:15]
	v_mov_b64_e32 v[70:71], s[28:29]
	v_add_u32_e32 v66, s12, v66
	v_and_b32_e32 v0, 7, v145
	v_mad_u64_u32 v[136:137], s[14:15], v68, s19, v[70:71]
	v_mad_i64_i32 v[138:139], s[12:13], v66, s19, v[70:71]
	v_mov_b32_e32 v118, 0
	v_and_b32_e32 v144, 64, v145
	v_lshlrev_b32_e32 v0, 4, v0
	v_mad_i32_i24 v137, v69, s19, v137
	s_mov_b32 s12, -2
	v_mov_b32_e32 v119, v118
	v_mov_b32_e32 v120, v118
	v_mov_b32_e32 v121, v118
	v_mov_b32_e32 v126, v118
	v_mov_b32_e32 v127, v118
	v_mov_b32_e32 v128, v118
	v_mov_b32_e32 v129, v118
	v_mov_b32_e32 v90, v118
	v_mov_b32_e32 v91, v118
	v_mov_b32_e32 v92, v118
	v_mov_b32_e32 v93, v118
	v_mov_b32_e32 v98, v118
	v_mov_b32_e32 v99, v118
	v_mov_b32_e32 v100, v118
	v_mov_b32_e32 v101, v118
	v_mov_b32_e32 v66, v118
	v_mov_b32_e32 v67, v118
	v_mov_b32_e32 v68, v118
	v_mov_b32_e32 v69, v118
	v_mov_b32_e32 v70, v118
	v_mov_b32_e32 v71, v118
	v_mov_b32_e32 v72, v118
	v_mov_b32_e32 v73, v118
	v_mov_b32_e32 v74, v118
	v_mov_b32_e32 v75, v118
	v_mov_b32_e32 v76, v118
	v_mov_b32_e32 v77, v118
	v_mov_b32_e32 v82, v118
	v_mov_b32_e32 v83, v118
	v_mov_b32_e32 v84, v118
	v_mov_b32_e32 v85, v118
	v_mov_b32_e32 v78, v118
	v_mov_b32_e32 v79, v118
	v_mov_b32_e32 v80, v118
	v_mov_b32_e32 v81, v118
	v_mov_b32_e32 v86, v118
	v_mov_b32_e32 v87, v118
	v_mov_b32_e32 v88, v118
	v_mov_b32_e32 v89, v118
	v_mov_b32_e32 v94, v118
	v_mov_b32_e32 v95, v118
	v_mov_b32_e32 v96, v118
	v_mov_b32_e32 v97, v118
	v_mov_b32_e32 v102, v118
	v_mov_b32_e32 v103, v118
	v_mov_b32_e32 v104, v118
	v_mov_b32_e32 v105, v118
	v_mov_b32_e32 v110, v118
	v_mov_b32_e32 v111, v118
	v_mov_b32_e32 v112, v118
	v_mov_b32_e32 v113, v118
	v_mov_b32_e32 v114, v118
	v_mov_b32_e32 v115, v118
	v_mov_b32_e32 v116, v118
	v_mov_b32_e32 v117, v118
	v_mov_b32_e32 v122, v118
	v_mov_b32_e32 v123, v118
	v_mov_b32_e32 v124, v118
	v_mov_b32_e32 v125, v118
	v_mov_b32_e32 v106, v118
	v_mov_b32_e32 v107, v118
	v_mov_b32_e32 v108, v118
	v_mov_b32_e32 v109, v118
	s_branch .LBB0_182
; DEV f32x4 mfma16(bf16x8 a, bf16x8 b, f32x4 c) { return __builtin_amdgcn_mfma_f32_16x16x32_bf16(a, b, c, 0, 0, 0); }
; #define G_LOAD(RA, RB, KT) { _Pragma("unroll") for (int i = 0; i < 4; i++) { \
;       RA[i] = *(const u32x4*)(Ap + (size_t)(i * 32) * lda + (KT) * 64); RB[i] = *(const u32x4*)(Bp + (size_t)(i * 32) * ldb + (KT) * 64); } }
; #define G_STORE(RA, RB) { _Pragma("unroll") for (int i = 0; i < 4; i++) { \
;       *(u32x4*)(As + (lrow + i * 32) * GLD + lcc * 8) = RA[i]; *(u32x4*)(Bs + (lrow + i * 32) * GLD + lcc * 8) = RB[i]; } }
; template <int TI, int TJ, int KS>
; DEV void mfma_lds(const bf16_t* Arows, int lda, const bf16_t* Brows, int ldb, int i0, int j0, f32x4 (&acc)[TI][TJ]) {
;     ...
;   for (int ks = 0; ks < KS; ks++) {
;     bf16x8 af[TI], bfr[TJ];
; #pragma unroll
;     for (int i = 0; i < TI; i++) af[i] = *(const bf16x8*)(Arows + (i0 + i * 16 + l15) * lda + ks * 32 + quad * 8);
; #pragma unroll
;     for (int j = 0; j < TJ; j++) bfr[j] = *(const bf16x8*)(Brows + (j0 + j * 16 + l15) * ldb + ks * 32 + quad * 8);
; #pragma unroll
;     for (int i = 0; i < TI; i++)
; #pragma unroll
;       for (int j = 0; j < TJ; j++) acc[i][j] = mfma16(af[i], bfr[j], acc[i][j]);
;   }
; template <class Epi>
; DEV void gemm_tile(const bf16_t* __restrict__ A, int lda, const bf16_t* __restrict__ Bt, int ldb, int K, int m0, int n0,
;                    Epi& epi, char* smem) {
;     ...
;   for (int kt = 0; kt < nk; kt += 2) {
;     __syncthreads();
;     G_STORE(ra0, rb0);
;     __syncthreads();
;     if (kt + 2 < nk) G_LOAD(ra0, rb0, kt + 2);
;     mfma_lds<4, 4, 2>(Bs, GLD, As, GLD, wn * 64, wm * 64, acc);
;     __syncthreads();
;     G_STORE(ra1, rb1);
;     __syncthreads();
;     if (kt + 3 < nk) G_LOAD(ra1, rb1, kt + 3);
;     mfma_lds<4, 4, 2>(Bs, GLD, As, GLD, wn * 64, wm * 64, acc);
.LBB0_181:
	v_mov_b32_e32 v130, v195
	v_and_b32_e32 v135, 15, v130
	v_or_b32_e32 v131, v135, v144
	v_and_b32_e32 v148, 48, v130
	v_mul_u32_u24_e32 v130, 0x50, v131
	v_lshl_add_u32 v147, v130, 1, v148
	v_or_b32_e32 v135, v135, v146
	v_mad_u32_u24 v238, v135, s36, v148
	v_lshl_add_u64 v[136:137], v[136:137], 0, s[34:35]
	v_lshl_add_u64 v[138:139], v[138:139], 0, s[34:35]
	s_andn2_b64 vcc, exec, s[14:15]
	ds_read_b128 v[148:151], v147 offset:20480
	ds_read_b128 v[164:167], v238
	ds_read_b128 v[168:171], v238 offset:2560
	ds_read_b128 v[172:175], v238 offset:5120
	ds_read_b128 v[176:179], v238 offset:7680
	ds_read_b128 v[152:155], v147 offset:23040
	ds_read_b128 v[156:159], v147 offset:25600
	ds_read_b128 v[160:163], v147 offset:28160
	ds_read_b128 v[180:183], v238 offset:64
	ds_read_b128 v[184:187], v238 offset:2624
	v_lshl_add_u64 v[188:189], v[188:189], 0, s[34:35]
	v_lshl_add_u64 v[190:191], v[190:191], 0, s[34:35]
	v_lshl_add_u64 v[192:193], v[192:193], 0, s[34:35]
	v_lshl_add_u64 v[236:237], v[236:237], 0, s[34:35]
	v_lshl_add_u64 v[240:241], v[240:241], 0, s[34:35]
	v_lshl_add_u64 v[242:243], v[242:243], 0, s[34:35]
	v_lshl_add_u64 v[244:245], v[244:245], 0, s[34:35]
	v_lshl_add_u64 v[246:247], v[246:247], 0, s[34:35]
	s_waitcnt lgkmcnt(8)
	v_mfma_f32_16x16x32_bf16 v[106:109], v[148:151], v[164:167], v[106:109]
	s_waitcnt lgkmcnt(7)
	v_mfma_f32_16x16x32_bf16 v[122:125], v[148:151], v[168:171], v[122:125]
	s_waitcnt lgkmcnt(6)
	v_mfma_f32_16x16x32_bf16 v[114:117], v[148:151], v[172:175], v[114:117]
	s_waitcnt lgkmcnt(5)
	v_mfma_f32_16x16x32_bf16 v[110:113], v[148:151], v[176:179], v[110:113]
	ds_read_b128 v[148:151], v147 offset:20544
	s_waitcnt lgkmcnt(5)
	v_mfma_f32_16x16x32_bf16 v[102:105], v[152:155], v[164:167], v[102:105]
	v_mfma_f32_16x16x32_bf16 v[94:97], v[152:155], v[168:171], v[94:97]
	v_mfma_f32_16x16x32_bf16 v[86:89], v[152:155], v[172:175], v[86:89]
	v_mfma_f32_16x16x32_bf16 v[78:81], v[152:155], v[176:179], v[78:81]
	ds_read_b128 v[152:155], v147 offset:23104
	s_waitcnt lgkmcnt(5)
	v_mfma_f32_16x16x32_bf16 v[82:85], v[156:159], v[164:167], v[82:85]
	v_mfma_f32_16x16x32_bf16 v[74:77], v[156:159], v[168:171], v[74:77]
	v_mfma_f32_16x16x32_bf16 v[70:73], v[156:159], v[172:175], v[70:73]
	v_mfma_f32_16x16x32_bf16 v[66:69], v[156:159], v[176:179], v[66:69]
	ds_read_b128 v[156:159], v147 offset:25664
	s_waitcnt lgkmcnt(5)
	v_mfma_f32_16x16x32_bf16 v[126:129], v[160:163], v[172:175], v[126:129]
	v_mfma_f32_16x16x32_bf16 v[118:121], v[160:163], v[176:179], v[118:121]
	ds_read_b128 v[172:175], v238 offset:5184
	ds_read_b128 v[176:179], v238 offset:7744
	v_mfma_f32_16x16x32_bf16 v[98:101], v[160:163], v[164:167], v[98:101]
	v_mfma_f32_16x16x32_bf16 v[90:93], v[160:163], v[168:171], v[90:93]
	ds_read_b128 v[160:163], v147 offset:28224
	s_waitcnt lgkmcnt(5)
	v_mfma_f32_16x16x32_bf16 v[106:109], v[148:151], v[180:183], v[106:109]
	s_waitcnt lgkmcnt(4)
	v_mfma_f32_16x16x32_bf16 v[102:105], v[152:155], v[180:183], v[102:105]
	s_waitcnt lgkmcnt(3)
	v_mfma_f32_16x16x32_bf16 v[82:85], v[156:159], v[180:183], v[82:85]
	v_mfma_f32_16x16x32_bf16 v[122:125], v[148:151], v[184:187], v[122:125]
	v_mfma_f32_16x16x32_bf16 v[94:97], v[152:155], v[184:187], v[94:97]
	v_mfma_f32_16x16x32_bf16 v[74:77], v[156:159], v[184:187], v[74:77]
	s_waitcnt lgkmcnt(2)
	v_mfma_f32_16x16x32_bf16 v[114:117], v[148:151], v[172:175], v[114:117]
	v_mfma_f32_16x16x32_bf16 v[86:89], v[152:155], v[172:175], v[86:89]
	v_mfma_f32_16x16x32_bf16 v[70:73], v[156:159], v[172:175], v[70:73]
	s_waitcnt lgkmcnt(1)
	v_mfma_f32_16x16x32_bf16 v[110:113], v[148:151], v[176:179], v[110:113]
	v_mfma_f32_16x16x32_bf16 v[78:81], v[152:155], v[176:179], v[78:81]
	v_mfma_f32_16x16x32_bf16 v[66:69], v[156:159], v[176:179], v[66:69]
	s_waitcnt lgkmcnt(0)
	v_mfma_f32_16x16x32_bf16 v[98:101], v[160:163], v[180:183], v[98:101]
	v_mfma_f32_16x16x32_bf16 v[90:93], v[160:163], v[184:187], v[90:93]
	v_mfma_f32_16x16x32_bf16 v[126:129], v[160:163], v[172:175], v[126:129]
	v_mfma_f32_16x16x32_bf16 v[118:121], v[160:163], v[176:179], v[118:121]
	s_cbranch_vccz .LBB0_177
.LBB0_182:
	s_add_i32 s12, s12, 2
	s_cmp_gt_u32 s12, 13
	s_cselect_b64 s[14:15], -1, 0
	s_and_b64 vcc, exec, s[14:15]
	v_lshl_add_u64 v[142:143], v[138:139], 0, v[0:1]
	v_lshl_add_u64 v[140:141], v[136:137], 0, v[0:1]
	s_waitcnt lgkmcnt(0)
	s_barrier
	s_waitcnt vmcnt(8)
	ds_write_b128 v134, v[2:5]
	ds_write_b128 v134, v[10:13] offset:20480
	ds_write_b128 v134, v[18:21] offset:5120
	ds_write_b128 v134, v[26:29] offset:25600
	ds_write_b128 v134, v[34:37] offset:10240
	ds_write_b128 v134, v[42:45] offset:30720
	ds_write_b128 v134, v[50:53] offset:15360
	ds_write_b128 v134, v[58:61] offset:35840
	s_waitcnt lgkmcnt(0)
	s_barrier
	s_cbranch_vccnz .Lgw_skip_0
	global_load_dwordx4 v[2:5], v[188:189], off offset:256
	global_load_dwordx4 v[10:13], v[190:191], off offset:256
	global_load_dwordx4 v[18:21], v[192:193], off offset:256
	global_load_dwordx4 v[26:29], v[236:237], off offset:256
	global_load_dwordx4 v[34:37], v[240:241], off offset:256
	global_load_dwordx4 v[42:45], v[242:243], off offset:256
	global_load_dwordx4 v[50:53], v[244:245], off offset:256
	global_load_dwordx4 v[58:61], v[246:247], off offset:256
; DEV f32x4 mfma16(bf16x8 a, bf16x8 b, f32x4 c) { return __builtin_amdgcn_mfma_f32_16x16x32_bf16(a, b, c, 0, 0, 0); }
; #define G_LOAD(RA, RB, KT) { _Pragma("unroll") for (int i = 0; i < 4; i++) { \
;       RA[i] = *(const u32x4*)(Ap + (size_t)(i * 32) * lda + (KT) * 64); RB[i] = *(const u32x4*)(Bp + (size_t)(i * 32) * ldb + (KT) * 64); } }
; #define G_STORE(RA, RB) { _Pragma("unroll") for (int i = 0; i < 4; i++) { \
;       *(u32x4*)(As + (lrow + i * 32) * GLD + lcc * 8) = RA[i]; *(u32x4*)(Bs + (lrow + i * 32) * GLD + lcc * 8) = RB[i]; } }
; template <int TI, int TJ, int KS>
; DEV void mfma_lds(const bf16_t* Arows, int lda, const bf16_t* Brows, int ldb, int i0, int j0, f32x4 (&acc)[TI][TJ]) {
;     ...
;   for (int ks = 0; ks < KS; ks++) {
;     bf16x8 af[TI], bfr[TJ];
; #pragma unroll
;     for (int i = 0; i < TI; i++) af[i] = *(const bf16x8*)(Arows + (i0 + i * 16 + l15) * lda + ks * 32 + quad * 8);
; #pragma unroll
;     for (int j = 0; j < TJ; j++) bfr[j] = *(const bf16x8*)(Brows + (j0 + j * 16 + l15) * ldb + ks * 32 + quad * 8);
; #pragma unroll
;     for (int i = 0; i < TI; i++)
; #pragma unroll
;       for (int j = 0; j < TJ; j++) acc[i][j] = mfma16(af[i], bfr[j], acc[i][j]);
;   }
; template <class Epi>
; DEV void gemm_tile(const bf16_t* __restrict__ A, int lda, const bf16_t* __restrict__ Bt, int ldb, int K, int m0, int n0,
;                    Epi& epi, char* smem) {
;     ...
;     mfma_lds<4, 4, 2>(Bs, GLD, As, GLD, wn * 64, wm * 64, acc);
;     __syncthreads();
;     G_STORE(ra1, rb1);
;     __syncthreads();
;     if (kt + 3 < nk) G_LOAD(ra1, rb1, kt + 3);
.LBB0_184:
	v_mov_b32_e32 v130, v195
	s_cmp_gt_u32 s12, 12
	v_and_b32_e32 v135, 15, v130
	v_or_b32_e32 v131, v135, v144
	v_and_b32_e32 v148, 48, v130
	v_mul_u32_u24_e32 v130, 0x50, v131
	v_lshl_add_u32 v147, v130, 1, v148
	v_or_b32_e32 v135, v135, v146
	v_mad_u32_u24 v238, v135, s36, v148
	ds_read_b128 v[148:151], v147 offset:20480
	ds_read_b128 v[164:167], v238
	ds_read_b128 v[168:171], v238 offset:2560
	ds_read_b128 v[172:175], v238 offset:5120
	ds_read_b128 v[176:179], v238 offset:7680
	ds_read_b128 v[152:155], v147 offset:23040
	ds_read_b128 v[156:159], v147 offset:25600
	ds_read_b128 v[160:163], v147 offset:28160
	ds_read_b128 v[180:183], v238 offset:64
	ds_read_b128 v[184:187], v238 offset:2624
	s_waitcnt lgkmcnt(8)
	v_mfma_f32_16x16x32_bf16 v[106:109], v[148:151], v[164:167], v[106:109]
	s_waitcnt lgkmcnt(7)
	v_mfma_f32_16x16x32_bf16 v[122:125], v[148:151], v[168:171], v[122:125]
	s_waitcnt lgkmcnt(6)
	v_mfma_f32_16x16x32_bf16 v[114:117], v[148:151], v[172:175], v[114:117]
	s_waitcnt lgkmcnt(5)
	v_mfma_f32_16x16x32_bf16 v[110:113], v[148:151], v[176:179], v[110:113]
	ds_read_b128 v[148:151], v147 offset:20544
	s_waitcnt lgkmcnt(5)
	v_mfma_f32_16x16x32_bf16 v[102:105], v[152:155], v[164:167], v[102:105]
	v_mfma_f32_16x16x32_bf16 v[94:97], v[152:155], v[168:171], v[94:97]
	v_mfma_f32_16x16x32_bf16 v[86:89], v[152:155], v[172:175], v[86:89]
	v_mfma_f32_16x16x32_bf16 v[78:81], v[152:155], v[176:179], v[78:81]
	ds_read_b128 v[152:155], v147 offset:23104
	s_waitcnt lgkmcnt(5)
	v_mfma_f32_16x16x32_bf16 v[82:85], v[156:159], v[164:167], v[82:85]
	v_mfma_f32_16x16x32_bf16 v[74:77], v[156:159], v[168:171], v[74:77]
	v_mfma_f32_16x16x32_bf16 v[70:73], v[156:159], v[172:175], v[70:73]
	v_mfma_f32_16x16x32_bf16 v[66:69], v[156:159], v[176:179], v[66:69]
	ds_read_b128 v[156:159], v147 offset:25664
	s_waitcnt lgkmcnt(5)
	v_mfma_f32_16x16x32_bf16 v[126:129], v[160:163], v[172:175], v[126:129]
	v_mfma_f32_16x16x32_bf16 v[118:121], v[160:163], v[176:179], v[118:121]
	ds_read_b128 v[172:175], v238 offset:5184
	ds_read_b128 v[176:179], v238 offset:7744
	v_mfma_f32_16x16x32_bf16 v[98:101], v[160:163], v[164:167], v[98:101]
	v_mfma_f32_16x16x32_bf16 v[90:93], v[160:163], v[168:171], v[90:93]
	ds_read_b128 v[160:163], v147 offset:28224
	s_waitcnt lgkmcnt(5)
	v_mfma_f32_16x16x32_bf16 v[106:109], v[148:151], v[180:183], v[106:109]
	s_waitcnt lgkmcnt(4)
	v_mfma_f32_16x16x32_bf16 v[102:105], v[152:155], v[180:183], v[102:105]
	s_waitcnt lgkmcnt(3)
	v_mfma_f32_16x16x32_bf16 v[82:85], v[156:159], v[180:183], v[82:85]
	v_mfma_f32_16x16x32_bf16 v[122:125], v[148:151], v[184:187], v[122:125]
	v_mfma_f32_16x16x32_bf16 v[94:97], v[152:155], v[184:187], v[94:97]
	v_mfma_f32_16x16x32_bf16 v[74:77], v[156:159], v[184:187], v[74:77]
	s_waitcnt lgkmcnt(2)
	v_mfma_f32_16x16x32_bf16 v[114:117], v[148:151], v[172:175], v[114:117]
	v_mfma_f32_16x16x32_bf16 v[86:89], v[152:155], v[172:175], v[86:89]
	v_mfma_f32_16x16x32_bf16 v[70:73], v[156:159], v[172:175], v[70:73]
	s_waitcnt lgkmcnt(1)
	v_mfma_f32_16x16x32_bf16 v[110:113], v[148:151], v[176:179], v[110:113]
	v_mfma_f32_16x16x32_bf16 v[78:81], v[152:155], v[176:179], v[78:81]
	v_mfma_f32_16x16x32_bf16 v[66:69], v[156:159], v[176:179], v[66:69]
	s_waitcnt lgkmcnt(0)
	v_mfma_f32_16x16x32_bf16 v[98:101], v[160:163], v[180:183], v[98:101]
	s_barrier
	v_mfma_f32_16x16x32_bf16 v[90:93], v[160:163], v[184:187], v[90:93]
	s_waitcnt vmcnt(8)
	ds_write_b128 v134, v[6:9]
	ds_write_b128 v134, v[14:17] offset:20480
	ds_write_b128 v134, v[22:25] offset:5120
	ds_write_b128 v134, v[30:33] offset:25600
	ds_write_b128 v134, v[38:41] offset:10240
	ds_write_b128 v134, v[46:49] offset:30720
	ds_write_b128 v134, v[54:57] offset:15360
	ds_write_b128 v134, v[62:65] offset:35840
	v_mfma_f32_16x16x32_bf16 v[126:129], v[160:163], v[172:175], v[126:129]
	s_waitcnt lgkmcnt(0)
	s_barrier
	v_mfma_f32_16x16x32_bf16 v[118:121], v[160:163], v[176:179], v[118:121]
	s_cbranch_scc1 .LBB0_181
	global_load_dwordx4 v[6:9], v[188:189], off offset:384
	global_load_dwordx4 v[14:17], v[190:191], off offset:384
	global_load_dwordx4 v[22:25], v[192:193], off offset:384
	global_load_dwordx4 v[30:33], v[236:237], off offset:384
	global_load_dwordx4 v[38:41], v[240:241], off offset:384
	global_load_dwordx4 v[46:49], v[242:243], off offset:384
	global_load_dwordx4 v[54:57], v[244:245], off offset:384
	global_load_dwordx4 v[62:65], v[246:247], off offset:384
	s_branch .LBB0_181

; DEV int tidx() { int t = threadIdx.x; asm volatile("" : "+v"(t)); return t; }
; #define G_LOAD(RA, RB, KT) { _Pragma("unroll") for (int i = 0; i < 4; i++) { \
;       RA[i] = *(const u32x4*)(Ap + (size_t)(i * 32) * lda + (KT) * 64); RB[i] = *(const u32x4*)(Bp + (size_t)(i * 32) * ldb + (KT) * 64); } }
; template <class Epi>
; DEV void gemm_tile(const bf16_t* __restrict__ A, int lda, const bf16_t* __restrict__ Bt, int ldb, int K, int m0, int n0,
;                    Epi& epi, char* smem) {
;   bf16_t* As = (bf16_t*)smem;
;   bf16_t* Bs = As + 128 * GLD;
;   const int tid = tidx(), lane = tid & 63, w = tid >> 6, wm = w >> 1, wn = w & 1;
;   const int l15 = lane & 15, quad = lane >> 4;
;   f32x4 acc[4][4];
; #pragma unroll
;   for (int i = 0; i < 4; i++)
; #pragma unroll
;     for (int j = 0; j < 4; j++) acc[i][j] = (f32x4){0.f, 0.f, 0.f, 0.f};
;   u32x4 ra0[4], rb0[4], ra1[4], rb1[4];
;   const int nk = K >> 6;
;   const int lrow = tid >> 3, lcc = tid & 7;
;   const bf16_t* Ap = A + (size_t)(m0 + lrow) * lda + lcc * 8;
;   const bf16_t* Bp = Bt + (size_t)(n0 + lrow) * ldb + lcc * 8;
;     ...
;   G_LOAD(ra0, rb0, 0);
;   G_LOAD(ra1, rb1, 1);
.LBB0_198:
	s_ashr_i32 s1, s12, 6
	s_and_b32 s0, s12, 7
	s_and_b32 s13, s1, 0x1ffffff8
	s_or_b32 s0, s13, s0
	s_lshl_b32 s0, s0, 3
	s_bfe_u32 s13, s12, 0x30006
	s_or_b32 s0, s0, s13
	s_cmpk_gt_i32 s0, 0x7f
	s_cbranch_scc1 .LBB0_197
	s_lshr_b32 s13, s12, 6
	v_mov_b32_e32 v141, v195
	s_bfe_u32 s16, s3, 0x30007
	s_and_b32 s20, s13, 7
	s_lshl_b32 s0, s0, 7
	s_lshl_b32 s13, s12, 4
	s_mul_i32 s18, s16, 0x44000
	v_ashrrev_i32_e32 v2, 3, v141
	s_and_b32 s16, s2, 7
	s_movk_i32 s21, 0x880
	s_and_b32 s13, s13, 0x380
	v_add_u32_e32 v0, s0, v2
	v_mov_b64_e32 v[4:5], s[14:15]
	s_lshl_b32 s19, s16, 3
	v_mad_i64_i32 v[4:5], s[16:17], v0, s21, v[4:5]
	v_lshlrev_b32_e32 v0, 4, v141
	v_add_u32_e32 v3, s13, v2
	v_mov_b64_e32 v[6:7], s[10:11]
	v_and_b32_e32 v0, 0x70, v0
	v_mad_i64_i32 v[6:7], s[16:17], v3, s21, v[6:7]
	v_lshl_add_u64 v[4:5], v[4:5], 0, v[0:1]
	s_mov_b32 s16, 0x11000
	v_add_co_u32_e32 v8, vcc, s16, v4
	v_lshl_add_u64 v[6:7], v[6:7], 0, v[0:1]
	s_nop 0
	v_addc_co_u32_e32 v9, vcc, 0, v5, vcc
	v_add_co_u32_e32 v10, vcc, s16, v6
	s_mov_b32 s16, 0x22000
	s_nop 0
	v_addc_co_u32_e32 v11, vcc, 0, v7, vcc
	v_add_co_u32_e32 v12, vcc, s16, v4
	v_ashrrev_i32_e32 v3, 1, v141
	s_nop 0
	v_addc_co_u32_e32 v13, vcc, 0, v5, vcc
	s_waitcnt vmcnt(22)
	v_add_co_u32_e32 v14, vcc, s16, v6
	s_mov_b32 s16, 0x33000
	s_nop 0
	v_addc_co_u32_e32 v15, vcc, 0, v7, vcc
	v_add_co_u32_e32 v16, vcc, s16, v4
	v_and_b32_e32 v142, 0xffffffc0, v3
	s_nop 0
	v_addc_co_u32_e32 v17, vcc, 0, v5, vcc
	v_add_co_u32_e32 v18, vcc, s16, v6
	v_mad_u64_u32 v[130:131], s[16:17], v2, s36, v[0:1]
	s_nop 0
	v_addc_co_u32_e32 v19, vcc, 0, v7, vcc
	global_load_dwordx4 v[42:45], v[4:5], off
	global_load_dwordx4 v[50:53], v[6:7], off
	global_load_dwordx4 v[58:61], v[8:9], off
	global_load_dwordx4 v[66:69], v[10:11], off
	global_load_dwordx4 v[78:81], v[12:13], off
	global_load_dwordx4 v[86:89], v[14:15], off
	global_load_dwordx4 v[94:97], v[16:17], off
	global_load_dwordx4 v[102:105], v[18:19], off
	v_mov_b64_e32 v[188:189], v[4:5]
	v_mov_b64_e32 v[190:191], v[6:7]
	v_mov_b64_e32 v[192:193], v[8:9]
	v_mov_b64_e32 v[236:237], v[10:11]
	v_mov_b64_e32 v[240:241], v[12:13]
	v_mov_b64_e32 v[242:243], v[14:15]
	v_mov_b64_e32 v[244:245], v[16:17]
	v_mov_b64_e32 v[246:247], v[18:19]
	global_load_dwordx4 v[46:49], v[4:5], off offset:128
	global_load_dwordx4 v[54:57], v[6:7], off offset:128
	global_load_dwordx4 v[62:65], v[8:9], off offset:128
	global_load_dwordx4 v[70:73], v[10:11], off offset:128
	global_load_dwordx4 v[82:85], v[12:13], off offset:128
	global_load_dwordx4 v[90:93], v[14:15], off offset:128
	global_load_dwordx4 v[98:101], v[16:17], off offset:128
	global_load_dwordx4 v[106:109], v[18:19], off offset:128
	s_add_u32 s16, s28, s18
	s_addc_u32 s17, s29, 0
	s_lshl_b32 s1, s1, 3
	s_and_b32 s1, s1, 0x1ffffc0
	v_mov_b64_e32 v[4:5], s[16:17]
	s_or_b32 s1, s1, s19
	v_mad_i64_i32 v[132:133], s[16:17], v2, s21, v[4:5]
	s_or_b32 s1, s1, s20
	s_lshl_b32 s16, s1, 7
	v_ashrrev_i32_e32 v3, 31, v2
	s_ashr_i32 s17, s16, 31
	v_lshl_add_u64 v[2:3], v[2:3], 0, s[16:17]
	v_mov_b64_e32 v[4:5], s[28:29]
	v_and_b32_e32 v0, 7, v141
	v_mad_u64_u32 v[134:135], s[16:17], v2, s21, v[4:5]
	v_mov_b32_e32 v2, 0
	v_and_b32_e32 v140, 64, v141
	v_lshlrev_b32_e32 v0, 4, v0
	v_mad_i32_i24 v135, v3, s21, v135
	s_movk_i32 s21, 0x2000
	s_mov_b32 s1, -2
	v_mov_b32_e32 v3, v2
	v_mov_b32_e32 v4, v2
	v_mov_b32_e32 v5, v2
	v_mov_b32_e32 v6, v2
	v_mov_b32_e32 v7, v2
	v_mov_b32_e32 v8, v2
	v_mov_b32_e32 v9, v2
	v_mov_b32_e32 v10, v2
	v_mov_b32_e32 v11, v2
	v_mov_b32_e32 v12, v2
	v_mov_b32_e32 v13, v2
	v_mov_b32_e32 v14, v2
	v_mov_b32_e32 v15, v2
	v_mov_b32_e32 v16, v2
	v_mov_b32_e32 v17, v2
	v_mov_b32_e32 v18, v2
	v_mov_b32_e32 v19, v2
	v_mov_b32_e32 v20, v2
	v_mov_b32_e32 v21, v2
	s_waitcnt vmcnt(37)
	v_mov_b32_e32 v22, v2
	v_mov_b32_e32 v23, v2
	v_mov_b32_e32 v24, v2
	v_mov_b32_e32 v25, v2
	v_mov_b32_e32 v26, v2
	v_mov_b32_e32 v27, v2
	v_mov_b32_e32 v28, v2
	v_mov_b32_e32 v29, v2
	s_waitcnt vmcnt(36)
	v_mov_b32_e32 v30, v2
	v_mov_b32_e32 v31, v2
	v_mov_b32_e32 v32, v2
	v_mov_b32_e32 v33, v2
	v_mov_b32_e32 v34, v2
	v_mov_b32_e32 v35, v2
	v_mov_b32_e32 v36, v2
	v_mov_b32_e32 v37, v2
	s_waitcnt vmcnt(35)
	v_mov_b32_e32 v38, v2
	v_mov_b32_e32 v39, v2
	v_mov_b32_e32 v40, v2
	v_mov_b32_e32 v41, v2
	v_mov_b32_e32 v74, v2
	v_mov_b32_e32 v75, v2
	v_mov_b32_e32 v76, v2
	v_mov_b32_e32 v77, v2
	v_mov_b32_e32 v110, v2
	v_mov_b32_e32 v111, v2
	v_mov_b32_e32 v112, v2
	v_mov_b32_e32 v113, v2
	v_mov_b32_e32 v114, v2
	v_mov_b32_e32 v115, v2
	v_mov_b32_e32 v116, v2
	v_mov_b32_e32 v117, v2
	v_mov_b32_e32 v118, v2
	v_mov_b32_e32 v119, v2
	v_mov_b32_e32 v120, v2
	v_mov_b32_e32 v121, v2
	v_mov_b32_e32 v122, v2
	v_mov_b32_e32 v123, v2
	v_mov_b32_e32 v124, v2
	v_mov_b32_e32 v125, v2
	v_mov_b32_e32 v126, v2
	v_mov_b32_e32 v127, v2
	v_mov_b32_e32 v128, v2
	v_mov_b32_e32 v129, v2
	s_branch .LBB0_201
; DEV f32x4 mfma16(bf16x8 a, bf16x8 b, f32x4 c) { return __builtin_amdgcn_mfma_f32_16x16x32_bf16(a, b, c, 0, 0, 0); }
; #define G_LOAD(RA, RB, KT) { _Pragma("unroll") for (int i = 0; i < 4; i++) { \
;       RA[i] = *(const u32x4*)(Ap + (size_t)(i * 32) * lda + (KT) * 64); RB[i] = *(const u32x4*)(Bp + (size_t)(i * 32) * ldb + (KT) * 64); } }
; #define G_STORE(RA, RB) { _Pragma("unroll") for (int i = 0; i < 4; i++) { \
;       *(u32x4*)(As + (lrow + i * 32) * GLD + lcc * 8) = RA[i]; *(u32x4*)(Bs + (lrow + i * 32) * GLD + lcc * 8) = RB[i]; } }
; template <int TI, int TJ, int KS>
; DEV void mfma_lds(const bf16_t* Arows, int lda, const bf16_t* Brows, int ldb, int i0, int j0, f32x4 (&acc)[TI][TJ]) {
;     ...
;   for (int ks = 0; ks < KS; ks++) {
;     bf16x8 af[TI], bfr[TJ];
; #pragma unroll
;     for (int i = 0; i < TI; i++) af[i] = *(const bf16x8*)(Arows + (i0 + i * 16 + l15) * lda + ks * 32 + quad * 8);
; #pragma unroll
;     for (int j = 0; j < TJ; j++) bfr[j] = *(const bf16x8*)(Brows + (j0 + j * 16 + l15) * ldb + ks * 32 + quad * 8);
; #pragma unroll
;     for (int i = 0; i < TI; i++)
; #pragma unroll
;       for (int j = 0; j < TJ; j++) acc[i][j] = mfma16(af[i], bfr[j], acc[i][j]);
;   }
; template <class Epi>
; DEV void gemm_tile(const bf16_t* __restrict__ A, int lda, const bf16_t* __restrict__ Bt, int ldb, int K, int m0, int n0,
;                    Epi& epi, char* smem) {
;     ...
;   for (int kt = 0; kt < nk; kt += 2) {
;     __syncthreads();
;     G_STORE(ra0, rb0);
;     __syncthreads();
;     if (kt + 2 < nk) G_LOAD(ra0, rb0, kt + 2);
;     mfma_lds<4, 4, 2>(Bs, GLD, As, GLD, wn * 64, wm * 64, acc);
;     __syncthreads();
;     G_STORE(ra1, rb1);
;     __syncthreads();
;     if (kt + 3 < nk) G_LOAD(ra1, rb1, kt + 3);
;     mfma_lds<4, 4, 2>(Bs, GLD, As, GLD, wn * 64, wm * 64, acc);
.LBB0_200:
	v_mov_b32_e32 v131, v195
	v_and_b32_e32 v143, 15, v131
	v_or_b32_e32 v144, v143, v140
	v_and_b32_e32 v148, 48, v131
	v_mul_u32_u24_e32 v131, 0x50, v144
	v_lshl_add_u32 v131, v131, 1, v148
	v_or_b32_e32 v143, v143, v142
	v_mad_u32_u24 v238, v143, s36, v148
	v_lshl_add_u64 v[132:133], v[132:133], 0, s[34:35]
	v_lshl_add_u64 v[134:135], v[134:135], 0, s[34:35]
	s_and_b64 vcc, exec, s[16:17]
	ds_read_b128 v[144:147], v131 offset:20480
	ds_read_b128 v[160:163], v238
	ds_read_b128 v[164:167], v238 offset:2560
	ds_read_b128 v[168:171], v238 offset:5120
	ds_read_b128 v[172:175], v238 offset:7680
	ds_read_b128 v[148:151], v131 offset:23040
	ds_read_b128 v[152:155], v131 offset:25600
	ds_read_b128 v[156:159], v131 offset:28160
	ds_read_b128 v[176:179], v238 offset:64
	ds_read_b128 v[180:183], v238 offset:2624
	v_lshl_add_u64 v[188:189], v[188:189], 0, s[34:35]
	v_lshl_add_u64 v[190:191], v[190:191], 0, s[34:35]
	v_lshl_add_u64 v[192:193], v[192:193], 0, s[34:35]
	v_lshl_add_u64 v[236:237], v[236:237], 0, s[34:35]
	v_lshl_add_u64 v[240:241], v[240:241], 0, s[34:35]
	v_lshl_add_u64 v[242:243], v[242:243], 0, s[34:35]
	v_lshl_add_u64 v[244:245], v[244:245], 0, s[34:35]
	v_lshl_add_u64 v[246:247], v[246:247], 0, s[34:35]
	s_waitcnt lgkmcnt(8)
	v_mfma_f32_16x16x32_bf16 v[126:129], v[144:147], v[160:163], v[126:129]
	s_waitcnt lgkmcnt(7)
	v_mfma_f32_16x16x32_bf16 v[122:125], v[144:147], v[164:167], v[122:125]
	s_waitcnt lgkmcnt(6)
	v_mfma_f32_16x16x32_bf16 v[118:121], v[144:147], v[168:171], v[118:121]
	s_waitcnt lgkmcnt(5)
	v_mfma_f32_16x16x32_bf16 v[114:117], v[144:147], v[172:175], v[114:117]
	ds_read_b128 v[144:147], v131 offset:20544
	s_waitcnt lgkmcnt(5)
	v_mfma_f32_16x16x32_bf16 v[110:113], v[148:151], v[160:163], v[110:113]
	v_mfma_f32_16x16x32_bf16 v[74:77], v[148:151], v[164:167], v[74:77]
	v_mfma_f32_16x16x32_bf16 v[38:41], v[148:151], v[168:171], v[38:41]
	v_mfma_f32_16x16x32_bf16 v[34:37], v[148:151], v[172:175], v[34:37]
	ds_read_b128 v[148:151], v131 offset:23104
	s_waitcnt lgkmcnt(5)
	v_mfma_f32_16x16x32_bf16 v[30:33], v[152:155], v[160:163], v[30:33]
	v_mfma_f32_16x16x32_bf16 v[26:29], v[152:155], v[164:167], v[26:29]
	v_mfma_f32_16x16x32_bf16 v[22:25], v[152:155], v[168:171], v[22:25]
	v_mfma_f32_16x16x32_bf16 v[18:21], v[152:155], v[172:175], v[18:21]
	ds_read_b128 v[152:155], v131 offset:25664
	s_waitcnt lgkmcnt(5)
	v_mfma_f32_16x16x32_bf16 v[6:9], v[156:159], v[168:171], v[6:9]
	v_mfma_f32_16x16x32_bf16 v[2:5], v[156:159], v[172:175], v[2:5]
	ds_read_b128 v[168:171], v238 offset:5184
	ds_read_b128 v[172:175], v238 offset:7744
	v_mfma_f32_16x16x32_bf16 v[14:17], v[156:159], v[160:163], v[14:17]
	v_mfma_f32_16x16x32_bf16 v[10:13], v[156:159], v[164:167], v[10:13]
	ds_read_b128 v[156:159], v131 offset:28224
	s_waitcnt lgkmcnt(5)
	v_mfma_f32_16x16x32_bf16 v[126:129], v[144:147], v[176:179], v[126:129]
	s_waitcnt lgkmcnt(4)
	v_mfma_f32_16x16x32_bf16 v[110:113], v[148:151], v[176:179], v[110:113]
	s_waitcnt lgkmcnt(3)
	v_mfma_f32_16x16x32_bf16 v[30:33], v[152:155], v[176:179], v[30:33]
	v_mfma_f32_16x16x32_bf16 v[122:125], v[144:147], v[180:183], v[122:125]
	v_mfma_f32_16x16x32_bf16 v[74:77], v[148:151], v[180:183], v[74:77]
	v_mfma_f32_16x16x32_bf16 v[26:29], v[152:155], v[180:183], v[26:29]
	s_waitcnt lgkmcnt(2)
	v_mfma_f32_16x16x32_bf16 v[118:121], v[144:147], v[168:171], v[118:121]
	v_mfma_f32_16x16x32_bf16 v[38:41], v[148:151], v[168:171], v[38:41]
	v_mfma_f32_16x16x32_bf16 v[22:25], v[152:155], v[168:171], v[22:25]
	s_waitcnt lgkmcnt(1)
	v_mfma_f32_16x16x32_bf16 v[114:117], v[144:147], v[172:175], v[114:117]
	v_mfma_f32_16x16x32_bf16 v[34:37], v[148:151], v[172:175], v[34:37]
	v_mfma_f32_16x16x32_bf16 v[18:21], v[152:155], v[172:175], v[18:21]
	s_waitcnt lgkmcnt(0)
	v_mfma_f32_16x16x32_bf16 v[14:17], v[156:159], v[176:179], v[14:17]
	v_mfma_f32_16x16x32_bf16 v[10:13], v[156:159], v[180:183], v[10:13]
	v_mfma_f32_16x16x32_bf16 v[6:9], v[156:159], v[168:171], v[6:9]
	v_mfma_f32_16x16x32_bf16 v[2:5], v[156:159], v[172:175], v[2:5]
	s_cbranch_vccnz .LBB0_205
.LBB0_201:
	s_add_i32 s1, s1, 2
	s_cmp_gt_u32 s1, 13
	s_cselect_b64 s[16:17], -1, 0
	s_and_b64 vcc, exec, s[16:17]
	v_lshl_add_u64 v[138:139], v[134:135], 0, v[0:1]
	v_lshl_add_u64 v[136:137], v[132:133], 0, v[0:1]
	s_waitcnt lgkmcnt(0)
	s_barrier
	s_waitcnt vmcnt(8)
	ds_write_b128 v130, v[42:45]
	ds_write_b128 v130, v[50:53] offset:20480
	ds_write_b128 v130, v[58:61] offset:5120
	ds_write_b128 v130, v[66:69] offset:25600
	ds_write_b128 v130, v[78:81] offset:10240
	ds_write_b128 v130, v[86:89] offset:30720
	ds_write_b128 v130, v[94:97] offset:15360
	ds_write_b128 v130, v[102:105] offset:35840
	s_waitcnt lgkmcnt(0)
	s_barrier
	s_cbranch_vccnz .Lgw_skip_1
	global_load_dwordx4 v[42:45], v[188:189], off offset:256
	global_load_dwordx4 v[50:53], v[190:191], off offset:256
	global_load_dwordx4 v[58:61], v[192:193], off offset:256
	global_load_dwordx4 v[66:69], v[236:237], off offset:256
	global_load_dwordx4 v[78:81], v[240:241], off offset:256
	global_load_dwordx4 v[86:89], v[242:243], off offset:256
	global_load_dwordx4 v[94:97], v[244:245], off offset:256
	global_load_dwordx4 v[102:105], v[246:247], off offset:256
; DEV f32x4 mfma16(bf16x8 a, bf16x8 b, f32x4 c) { return __builtin_amdgcn_mfma_f32_16x16x32_bf16(a, b, c, 0, 0, 0); }
; #define G_LOAD(RA, RB, KT) { _Pragma("unroll") for (int i = 0; i < 4; i++) { \
;       RA[i] = *(const u32x4*)(Ap + (size_t)(i * 32) * lda + (KT) * 64); RB[i] = *(const u32x4*)(Bp + (size_t)(i * 32) * ldb + (KT) * 64); } }
; #define G_STORE(RA, RB) { _Pragma("unroll") for (int i = 0; i < 4; i++) { \
;       *(u32x4*)(As + (lrow + i * 32) * GLD + lcc * 8) = RA[i]; *(u32x4*)(Bs + (lrow + i * 32) * GLD + lcc * 8) = RB[i]; } }
; template <int TI, int TJ, int KS>
; DEV void mfma_lds(const bf16_t* Arows, int lda, const bf16_t* Brows, int ldb, int i0, int j0, f32x4 (&acc)[TI][TJ]) {
;     ...
;   for (int ks = 0; ks < KS; ks++) {
;     bf16x8 af[TI], bfr[TJ];
; #pragma unroll
;     for (int i = 0; i < TI; i++) af[i] = *(const bf16x8*)(Arows + (i0 + i * 16 + l15) * lda + ks * 32 + quad * 8);
; #pragma unroll
;     for (int j = 0; j < TJ; j++) bfr[j] = *(const bf16x8*)(Brows + (j0 + j * 16 + l15) * ldb + ks * 32 + quad * 8);
; #pragma unroll
;     for (int i = 0; i < TI; i++)
; #pragma unroll
;       for (int j = 0; j < TJ; j++) acc[i][j] = mfma16(af[i], bfr[j], acc[i][j]);
;   }
; template <class Epi>
; DEV void gemm_tile(const bf16_t* __restrict__ A, int lda, const bf16_t* __restrict__ Bt, int ldb, int K, int m0, int n0,
;                    Epi& epi, char* smem) {
;     ...
;     mfma_lds<4, 4, 2>(Bs, GLD, As, GLD, wn * 64, wm * 64, acc);
;     __syncthreads();
;     G_STORE(ra1, rb1);
;     __syncthreads();
;     if (kt + 3 < nk) G_LOAD(ra1, rb1, kt + 3);
.LBB0_203:
	v_mov_b32_e32 v131, v195
	s_cmp_gt_u32 s1, 12
	v_and_b32_e32 v143, 15, v131
	v_or_b32_e32 v144, v143, v140
	v_and_b32_e32 v148, 48, v131
	v_mul_u32_u24_e32 v131, 0x50, v144
	v_lshl_add_u32 v131, v131, 1, v148
	v_or_b32_e32 v143, v143, v142
	v_mad_u32_u24 v238, v143, s36, v148
	ds_read_b128 v[144:147], v131 offset:20480
	ds_read_b128 v[160:163], v238
	ds_read_b128 v[164:167], v238 offset:2560
	ds_read_b128 v[168:171], v238 offset:5120
	ds_read_b128 v[172:175], v238 offset:7680
	ds_read_b128 v[148:151], v131 offset:23040
	ds_read_b128 v[152:155], v131 offset:25600
	ds_read_b128 v[156:159], v131 offset:28160
	ds_read_b128 v[176:179], v238 offset:64
	ds_read_b128 v[180:183], v238 offset:2624
	s_waitcnt lgkmcnt(8)
	v_mfma_f32_16x16x32_bf16 v[126:129], v[144:147], v[160:163], v[126:129]
	s_waitcnt lgkmcnt(7)
	v_mfma_f32_16x16x32_bf16 v[122:125], v[144:147], v[164:167], v[122:125]
	s_waitcnt lgkmcnt(6)
	v_mfma_f32_16x16x32_bf16 v[118:121], v[144:147], v[168:171], v[118:121]
	s_waitcnt lgkmcnt(5)
	v_mfma_f32_16x16x32_bf16 v[114:117], v[144:147], v[172:175], v[114:117]
	ds_read_b128 v[144:147], v131 offset:20544
	s_waitcnt lgkmcnt(5)
	v_mfma_f32_16x16x32_bf16 v[110:113], v[148:151], v[160:163], v[110:113]
	v_mfma_f32_16x16x32_bf16 v[74:77], v[148:151], v[164:167], v[74:77]
	v_mfma_f32_16x16x32_bf16 v[38:41], v[148:151], v[168:171], v[38:41]
	v_mfma_f32_16x16x32_bf16 v[34:37], v[148:151], v[172:175], v[34:37]
	ds_read_b128 v[148:151], v131 offset:23104
	s_waitcnt lgkmcnt(5)
	v_mfma_f32_16x16x32_bf16 v[30:33], v[152:155], v[160:163], v[30:33]
	v_mfma_f32_16x16x32_bf16 v[26:29], v[152:155], v[164:167], v[26:29]
	v_mfma_f32_16x16x32_bf16 v[22:25], v[152:155], v[168:171], v[22:25]
	v_mfma_f32_16x16x32_bf16 v[18:21], v[152:155], v[172:175], v[18:21]
	ds_read_b128 v[152:155], v131 offset:25664
	s_waitcnt lgkmcnt(5)
	v_mfma_f32_16x16x32_bf16 v[6:9], v[156:159], v[168:171], v[6:9]
	v_mfma_f32_16x16x32_bf16 v[2:5], v[156:159], v[172:175], v[2:5]
	ds_read_b128 v[168:171], v238 offset:5184
	ds_read_b128 v[172:175], v238 offset:7744
	v_mfma_f32_16x16x32_bf16 v[14:17], v[156:159], v[160:163], v[14:17]
	v_mfma_f32_16x16x32_bf16 v[10:13], v[156:159], v[164:167], v[10:13]
	ds_read_b128 v[156:159], v131 offset:28224
	s_waitcnt lgkmcnt(5)
	v_mfma_f32_16x16x32_bf16 v[126:129], v[144:147], v[176:179], v[126:129]
	s_waitcnt lgkmcnt(4)
	v_mfma_f32_16x16x32_bf16 v[110:113], v[148:151], v[176:179], v[110:113]
	s_waitcnt lgkmcnt(3)
	v_mfma_f32_16x16x32_bf16 v[30:33], v[152:155], v[176:179], v[30:33]
	v_mfma_f32_16x16x32_bf16 v[122:125], v[144:147], v[180:183], v[122:125]
	v_mfma_f32_16x16x32_bf16 v[74:77], v[148:151], v[180:183], v[74:77]
	v_mfma_f32_16x16x32_bf16 v[26:29], v[152:155], v[180:183], v[26:29]
	s_waitcnt lgkmcnt(2)
	v_mfma_f32_16x16x32_bf16 v[118:121], v[144:147], v[168:171], v[118:121]
	v_mfma_f32_16x16x32_bf16 v[38:41], v[148:151], v[168:171], v[38:41]
	v_mfma_f32_16x16x32_bf16 v[22:25], v[152:155], v[168:171], v[22:25]
	s_waitcnt lgkmcnt(1)
	v_mfma_f32_16x16x32_bf16 v[114:117], v[144:147], v[172:175], v[114:117]
	v_mfma_f32_16x16x32_bf16 v[34:37], v[148:151], v[172:175], v[34:37]
	v_mfma_f32_16x16x32_bf16 v[18:21], v[152:155], v[172:175], v[18:21]
	s_waitcnt lgkmcnt(0)
	v_mfma_f32_16x16x32_bf16 v[14:17], v[156:159], v[176:179], v[14:17]
	s_barrier
	v_mfma_f32_16x16x32_bf16 v[10:13], v[156:159], v[180:183], v[10:13]
	s_waitcnt vmcnt(8)
	ds_write_b128 v130, v[46:49]
	ds_write_b128 v130, v[54:57] offset:20480
	ds_write_b128 v130, v[62:65] offset:5120
	ds_write_b128 v130, v[70:73] offset:25600
	ds_write_b128 v130, v[82:85] offset:10240
	ds_write_b128 v130, v[90:93] offset:30720
	ds_write_b128 v130, v[98:101] offset:15360
	ds_write_b128 v130, v[106:109] offset:35840
	v_mfma_f32_16x16x32_bf16 v[6:9], v[156:159], v[168:171], v[6:9]
	s_waitcnt lgkmcnt(0)
	s_barrier
	v_mfma_f32_16x16x32_bf16 v[2:5], v[156:159], v[172:175], v[2:5]
	s_cbranch_scc1 .LBB0_200
	global_load_dwordx4 v[46:49], v[188:189], off offset:384
	global_load_dwordx4 v[54:57], v[190:191], off offset:384
	global_load_dwordx4 v[62:65], v[192:193], off offset:384
	global_load_dwordx4 v[70:73], v[236:237], off offset:384
	global_load_dwordx4 v[82:85], v[240:241], off offset:384
	global_load_dwordx4 v[90:93], v[242:243], off offset:384
	global_load_dwordx4 v[98:101], v[244:245], off offset:384
	global_load_dwordx4 v[106:109], v[246:247], off offset:384
	s_branch .LBB0_200

; DEV int tidx() { int t = threadIdx.x; asm volatile("" : "+v"(t)); return t; }
; #define G_LOAD(RA, RB, KT) { _Pragma("unroll") for (int i = 0; i < 4; i++) { \
;       RA[i] = *(const u32x4*)(Ap + (size_t)(i * 32) * lda + (KT) * 64); RB[i] = *(const u32x4*)(Bp + (size_t)(i * 32) * ldb + (KT) * 64); } }
; template <class Epi>
; DEV void gemm_tile(const bf16_t* __restrict__ A, int lda, const bf16_t* __restrict__ Bt, int ldb, int K, int m0, int n0,
;                    Epi& epi, char* smem) {
;   bf16_t* As = (bf16_t*)smem;
;   bf16_t* Bs = As + 128 * GLD;
;   const int tid = tidx(), lane = tid & 63, w = tid >> 6, wm = w >> 1, wn = w & 1;
;   const int l15 = lane & 15, quad = lane >> 4;
;   f32x4 acc[4][4];
; #pragma unroll
;   for (int i = 0; i < 4; i++)
; #pragma unroll
;     for (int j = 0; j < 4; j++) acc[i][j] = (f32x4){0.f, 0.f, 0.f, 0.f};
;   u32x4 ra0[4], rb0[4], ra1[4], rb1[4];
;   const int nk = K >> 6;
;   const int lrow = tid >> 3, lcc = tid & 7;
;   const bf16_t* Ap = A + (size_t)(m0 + lrow) * lda + lcc * 8;
;   const bf16_t* Bp = Bt + (size_t)(n0 + lrow) * ldb + lcc * 8;
;     ...
;   G_LOAD(ra0, rb0, 0);
;   G_LOAD(ra1, rb1, 1);
.LBB0_644:
	s_ashr_i32 s9, s11, 6
	s_and_b32 s8, s11, 7
	s_and_b32 s12, s9, -8
	s_or_b32 s12, s12, s8
	s_lshr_b32 s8, s11, 31
	s_add_i32 s8, s12, s8
	s_ashr_i32 s8, s8, 1
	s_lshl_b32 s13, s8, 3
	s_bfe_u32 s14, s11, 0x30006
	s_or_b32 s13, s13, s14
	s_cmpk_gt_i32 s13, 0x83
	s_cbranch_scc1 .LBB0_643
	v_mov_b32_e32 v145, v195
	s_lshr_b32 s14, s11, 6
	s_lshl_b32 s12, s12, 3
	s_lshl_b32 s18, s8, 4
	s_lshl_b32 s13, s13, 7
	s_and_b32 s15, s10, 7
	v_ashrrev_i32_e32 v66, 3, v145
	s_and_b32 s14, s14, 7
	s_sub_i32 s12, s12, s18
	s_movk_i32 s20, 0x880
	s_bfe_u32 s19, s11, 0x30003
	v_add_u32_e32 v0, s13, v66
	v_mov_b64_e32 v[2:3], s[6:7]
	s_lshl_b32 s16, s15, 3
	s_lshl_b32 s17, s14, 7
	s_or_b32 s12, s12, s19
	v_mad_i64_i32 v[2:3], s[14:15], v0, s20, v[2:3]
	v_lshlrev_b32_e32 v0, 4, v145
	s_lshl_b32 s12, s12, 7
	v_and_b32_e32 v0, 0x70, v0
	v_lshl_add_u64 v[6:7], v[2:3], 0, v[0:1]
	v_add_u32_e32 v4, s12, v66
	v_mov_b64_e32 v[2:3], s[2:3]
	v_mad_i64_i32 v[2:3], s[14:15], v4, s20, v[2:3]
	s_mov_b32 s14, 0x11000
	s_waitcnt vmcnt(21)
	v_add_co_u32_e32 v22, vcc, s14, v6
	v_lshl_add_u64 v[14:15], v[2:3], 0, v[0:1]
	s_nop 0
	v_addc_co_u32_e32 v23, vcc, 0, v7, vcc
	s_waitcnt vmcnt(20)
	v_add_co_u32_e32 v30, vcc, s14, v14
	s_mov_b32 s14, 0x22000
	s_nop 0
	v_addc_co_u32_e32 v31, vcc, 0, v15, vcc
	s_waitcnt vmcnt(19)
	v_add_co_u32_e32 v38, vcc, s14, v6
	s_lshl_b32 s9, s9, 3
	s_nop 0
	v_addc_co_u32_e32 v39, vcc, 0, v7, vcc
	s_waitcnt vmcnt(18)
	v_add_co_u32_e32 v46, vcc, s14, v14
	s_mov_b32 s14, 0x33000
	s_nop 0
	v_addc_co_u32_e32 v47, vcc, 0, v15, vcc
	s_waitcnt vmcnt(17)
	v_add_co_u32_e32 v54, vcc, s14, v6
	s_and_b32 s9, s9, 0x1ffffc0
	s_nop 0
	v_addc_co_u32_e32 v55, vcc, 0, v7, vcc
	s_waitcnt vmcnt(16)
	v_add_co_u32_e32 v62, vcc, s14, v14
	s_or_b32 s9, s9, s16
	s_nop 0
	v_addc_co_u32_e32 v63, vcc, 0, v15, vcc
	global_load_dwordx4 v[2:5], v[6:7], off
	s_nop 0
	global_load_dwordx4 v[10:13], v[14:15], off
	s_nop 0
	global_load_dwordx4 v[18:21], v[22:23], off
	s_nop 0
	global_load_dwordx4 v[26:29], v[30:31], off
	s_nop 0
	global_load_dwordx4 v[34:37], v[38:39], off
	s_nop 0
	global_load_dwordx4 v[42:45], v[46:47], off
	s_nop 0
	global_load_dwordx4 v[50:53], v[54:55], off
	s_nop 0
	global_load_dwordx4 v[58:61], v[62:63], off
	s_nop 0
	v_mov_b64_e32 v[188:189], v[6:7]
	v_mov_b64_e32 v[190:191], v[14:15]
	v_mov_b64_e32 v[192:193], v[22:23]
	v_mov_b64_e32 v[236:237], v[30:31]
	v_mov_b64_e32 v[240:241], v[38:39]
	v_mov_b64_e32 v[242:243], v[46:47]
	v_mov_b64_e32 v[244:245], v[54:55]
	v_mov_b64_e32 v[246:247], v[62:63]
	global_load_dwordx4 v[6:9], v[6:7], off offset:128
	s_nop 0
	global_load_dwordx4 v[14:17], v[14:15], off offset:128
	s_nop 0
	global_load_dwordx4 v[22:25], v[22:23], off offset:128
	s_nop 0
	global_load_dwordx4 v[30:33], v[30:31], off offset:128
	s_nop 0
	global_load_dwordx4 v[38:41], v[38:39], off offset:128
	s_nop 0
	global_load_dwordx4 v[46:49], v[46:47], off offset:128
	s_nop 0
	global_load_dwordx4 v[54:57], v[54:55], off offset:128
	s_nop 0
	global_load_dwordx4 v[62:65], v[62:63], off offset:128
	s_or_b32 s9, s9, s19
	v_mad_u64_u32 v[134:135], s[14:15], v66, s36, v[0:1]
	s_sub_i32 s9, s9, s18
	v_ashrrev_i32_e32 v67, 1, v145
	s_lshl_b32 s14, s9, 7
	v_and_b32_e32 v146, 0xffffffc0, v67
	v_ashrrev_i32_e32 v67, 31, v66
	s_ashr_i32 s15, s14, 31
	s_lshl_b32 s8, s8, 10
	s_movk_i32 s19, 0x880
	v_lshl_add_u64 v[68:69], v[66:67], 0, s[14:15]
	v_mov_b64_e32 v[70:71], s[28:29]
	s_or_b32 s8, s17, s8
	v_and_b32_e32 v0, 7, v145
	v_mad_u64_u32 v[136:137], s[14:15], v68, s19, v[70:71]
	v_add_u32_e32 v66, s8, v66
	v_mov_b32_e32 v118, 0
	v_and_b32_e32 v144, 64, v145
	v_lshlrev_b32_e32 v0, 4, v0
	v_mad_i32_i24 v137, v69, s19, v137
	v_mad_i64_i32 v[138:139], s[8:9], v66, s19, v[70:71]
	s_mov_b32 s14, -2
	v_mov_b32_e32 v119, v118
	v_mov_b32_e32 v120, v118
	v_mov_b32_e32 v121, v118
	v_mov_b32_e32 v126, v118
	v_mov_b32_e32 v127, v118
	v_mov_b32_e32 v128, v118
	v_mov_b32_e32 v129, v118
	v_mov_b32_e32 v90, v118
	v_mov_b32_e32 v91, v118
	v_mov_b32_e32 v92, v118
	v_mov_b32_e32 v93, v118
	v_mov_b32_e32 v98, v118
	v_mov_b32_e32 v99, v118
	v_mov_b32_e32 v100, v118
	v_mov_b32_e32 v101, v118
	v_mov_b32_e32 v66, v118
	v_mov_b32_e32 v67, v118
	v_mov_b32_e32 v68, v118
	v_mov_b32_e32 v69, v118
	v_mov_b32_e32 v70, v118
	v_mov_b32_e32 v71, v118
	v_mov_b32_e32 v72, v118
	v_mov_b32_e32 v73, v118
	v_mov_b32_e32 v74, v118
	v_mov_b32_e32 v75, v118
	v_mov_b32_e32 v76, v118
	v_mov_b32_e32 v77, v118
	v_mov_b32_e32 v82, v118
	v_mov_b32_e32 v83, v118
	v_mov_b32_e32 v84, v118
	v_mov_b32_e32 v85, v118
	v_mov_b32_e32 v78, v118
	v_mov_b32_e32 v79, v118
	v_mov_b32_e32 v80, v118
	v_mov_b32_e32 v81, v118
	v_mov_b32_e32 v86, v118
	v_mov_b32_e32 v87, v118
	v_mov_b32_e32 v88, v118
	v_mov_b32_e32 v89, v118
	v_mov_b32_e32 v94, v118
	v_mov_b32_e32 v95, v118
	v_mov_b32_e32 v96, v118
	v_mov_b32_e32 v97, v118
	v_mov_b32_e32 v102, v118
	v_mov_b32_e32 v103, v118
	v_mov_b32_e32 v104, v118
	v_mov_b32_e32 v105, v118
	v_mov_b32_e32 v110, v118
	v_mov_b32_e32 v111, v118
	v_mov_b32_e32 v112, v118
	v_mov_b32_e32 v113, v118
	v_mov_b32_e32 v114, v118
	v_mov_b32_e32 v115, v118
	v_mov_b32_e32 v116, v118
	v_mov_b32_e32 v117, v118
	v_mov_b32_e32 v122, v118
	v_mov_b32_e32 v123, v118
	v_mov_b32_e32 v124, v118
	v_mov_b32_e32 v125, v118
	v_mov_b32_e32 v106, v118
	v_mov_b32_e32 v107, v118
	v_mov_b32_e32 v108, v118
	v_mov_b32_e32 v109, v118
	s_branch .LBB0_647
; DEV f32x4 mfma16(bf16x8 a, bf16x8 b, f32x4 c) { return __builtin_amdgcn_mfma_f32_16x16x32_bf16(a, b, c, 0, 0, 0); }
; #define G_LOAD(RA, RB, KT) { _Pragma("unroll") for (int i = 0; i < 4; i++) { \
;       RA[i] = *(const u32x4*)(Ap + (size_t)(i * 32) * lda + (KT) * 64); RB[i] = *(const u32x4*)(Bp + (size_t)(i * 32) * ldb + (KT) * 64); } }
; #define G_STORE(RA, RB) { _Pragma("unroll") for (int i = 0; i < 4; i++) { \
;       *(u32x4*)(As + (lrow + i * 32) * GLD + lcc * 8) = RA[i]; *(u32x4*)(Bs + (lrow + i * 32) * GLD + lcc * 8) = RB[i]; } }
; template <int TI, int TJ, int KS>
; DEV void mfma_lds(const bf16_t* Arows, int lda, const bf16_t* Brows, int ldb, int i0, int j0, f32x4 (&acc)[TI][TJ]) {
;     ...
;   for (int ks = 0; ks < KS; ks++) {
;     bf16x8 af[TI], bfr[TJ];
; #pragma unroll
;     for (int i = 0; i < TI; i++) af[i] = *(const bf16x8*)(Arows + (i0 + i * 16 + l15) * lda + ks * 32 + quad * 8);
; #pragma unroll
;     for (int j = 0; j < TJ; j++) bfr[j] = *(const bf16x8*)(Brows + (j0 + j * 16 + l15) * ldb + ks * 32 + quad * 8);
; #pragma unroll
;     for (int i = 0; i < TI; i++)
; #pragma unroll
;       for (int j = 0; j < TJ; j++) acc[i][j] = mfma16(af[i], bfr[j], acc[i][j]);
;   }
; template <class Epi>
; DEV void gemm_tile(const bf16_t* __restrict__ A, int lda, const bf16_t* __restrict__ Bt, int ldb, int K, int m0, int n0,
;                    Epi& epi, char* smem) {
;     ...
;   for (int kt = 0; kt < nk; kt += 2) {
;     __syncthreads();
;     G_STORE(ra0, rb0);
;     __syncthreads();
;     if (kt + 2 < nk) G_LOAD(ra0, rb0, kt + 2);
;     mfma_lds<4, 4, 2>(Bs, GLD, As, GLD, wn * 64, wm * 64, acc);
;     __syncthreads();
;     G_STORE(ra1, rb1);
;     __syncthreads();
;     if (kt + 3 < nk) G_LOAD(ra1, rb1, kt + 3);
;     mfma_lds<4, 4, 2>(Bs, GLD, As, GLD, wn * 64, wm * 64, acc);
.LBB0_646:
	v_mov_b32_e32 v130, v195
	v_and_b32_e32 v135, 15, v130
	v_or_b32_e32 v131, v135, v144
	v_and_b32_e32 v148, 48, v130
	v_mul_u32_u24_e32 v130, 0x50, v131
	v_lshl_add_u32 v147, v130, 1, v148
	v_or_b32_e32 v135, v135, v146
	v_mad_u32_u24 v238, v135, s36, v148
	v_lshl_add_u64 v[136:137], v[136:137], 0, s[34:35]
	v_lshl_add_u64 v[138:139], v[138:139], 0, s[34:35]
	s_andn2_b64 vcc, exec, s[8:9]
	ds_read_b128 v[148:151], v147 offset:20480
	ds_read_b128 v[164:167], v238
	ds_read_b128 v[168:171], v238 offset:2560
	ds_read_b128 v[172:175], v238 offset:5120
	ds_read_b128 v[176:179], v238 offset:7680
	ds_read_b128 v[152:155], v147 offset:23040
	ds_read_b128 v[156:159], v147 offset:25600
	ds_read_b128 v[160:163], v147 offset:28160
	ds_read_b128 v[180:183], v238 offset:64
	ds_read_b128 v[184:187], v238 offset:2624
	v_lshl_add_u64 v[188:189], v[188:189], 0, s[34:35]
	v_lshl_add_u64 v[190:191], v[190:191], 0, s[34:35]
	v_lshl_add_u64 v[192:193], v[192:193], 0, s[34:35]
	v_lshl_add_u64 v[236:237], v[236:237], 0, s[34:35]
	v_lshl_add_u64 v[240:241], v[240:241], 0, s[34:35]
	v_lshl_add_u64 v[242:243], v[242:243], 0, s[34:35]
	v_lshl_add_u64 v[244:245], v[244:245], 0, s[34:35]
	v_lshl_add_u64 v[246:247], v[246:247], 0, s[34:35]
	s_waitcnt lgkmcnt(8)
	v_mfma_f32_16x16x32_bf16 v[106:109], v[148:151], v[164:167], v[106:109]
	s_waitcnt lgkmcnt(7)
	v_mfma_f32_16x16x32_bf16 v[122:125], v[148:151], v[168:171], v[122:125]
	s_waitcnt lgkmcnt(6)
	v_mfma_f32_16x16x32_bf16 v[114:117], v[148:151], v[172:175], v[114:117]
	s_waitcnt lgkmcnt(5)
	v_mfma_f32_16x16x32_bf16 v[110:113], v[148:151], v[176:179], v[110:113]
	ds_read_b128 v[148:151], v147 offset:20544
	s_waitcnt lgkmcnt(5)
	v_mfma_f32_16x16x32_bf16 v[102:105], v[152:155], v[164:167], v[102:105]
	v_mfma_f32_16x16x32_bf16 v[94:97], v[152:155], v[168:171], v[94:97]
	v_mfma_f32_16x16x32_bf16 v[86:89], v[152:155], v[172:175], v[86:89]
	v_mfma_f32_16x16x32_bf16 v[78:81], v[152:155], v[176:179], v[78:81]
	ds_read_b128 v[152:155], v147 offset:23104
	s_waitcnt lgkmcnt(5)
	v_mfma_f32_16x16x32_bf16 v[82:85], v[156:159], v[164:167], v[82:85]
	v_mfma_f32_16x16x32_bf16 v[74:77], v[156:159], v[168:171], v[74:77]
	v_mfma_f32_16x16x32_bf16 v[70:73], v[156:159], v[172:175], v[70:73]
	v_mfma_f32_16x16x32_bf16 v[66:69], v[156:159], v[176:179], v[66:69]
	ds_read_b128 v[156:159], v147 offset:25664
	s_waitcnt lgkmcnt(5)
	v_mfma_f32_16x16x32_bf16 v[126:129], v[160:163], v[172:175], v[126:129]
	v_mfma_f32_16x16x32_bf16 v[118:121], v[160:163], v[176:179], v[118:121]
	ds_read_b128 v[172:175], v238 offset:5184
	ds_read_b128 v[176:179], v238 offset:7744
	v_mfma_f32_16x16x32_bf16 v[98:101], v[160:163], v[164:167], v[98:101]
	v_mfma_f32_16x16x32_bf16 v[90:93], v[160:163], v[168:171], v[90:93]
	ds_read_b128 v[160:163], v147 offset:28224
	s_waitcnt lgkmcnt(5)
	v_mfma_f32_16x16x32_bf16 v[106:109], v[148:151], v[180:183], v[106:109]
	s_waitcnt lgkmcnt(4)
	v_mfma_f32_16x16x32_bf16 v[102:105], v[152:155], v[180:183], v[102:105]
	s_waitcnt lgkmcnt(3)
	v_mfma_f32_16x16x32_bf16 v[82:85], v[156:159], v[180:183], v[82:85]
	v_mfma_f32_16x16x32_bf16 v[122:125], v[148:151], v[184:187], v[122:125]
	v_mfma_f32_16x16x32_bf16 v[94:97], v[152:155], v[184:187], v[94:97]
	v_mfma_f32_16x16x32_bf16 v[74:77], v[156:159], v[184:187], v[74:77]
	s_waitcnt lgkmcnt(2)
	v_mfma_f32_16x16x32_bf16 v[114:117], v[148:151], v[172:175], v[114:117]
	v_mfma_f32_16x16x32_bf16 v[86:89], v[152:155], v[172:175], v[86:89]
	v_mfma_f32_16x16x32_bf16 v[70:73], v[156:159], v[172:175], v[70:73]
	s_waitcnt lgkmcnt(1)
	v_mfma_f32_16x16x32_bf16 v[110:113], v[148:151], v[176:179], v[110:113]
	v_mfma_f32_16x16x32_bf16 v[78:81], v[152:155], v[176:179], v[78:81]
	v_mfma_f32_16x16x32_bf16 v[66:69], v[156:159], v[176:179], v[66:69]
	s_waitcnt lgkmcnt(0)
	v_mfma_f32_16x16x32_bf16 v[98:101], v[160:163], v[180:183], v[98:101]
	v_mfma_f32_16x16x32_bf16 v[90:93], v[160:163], v[184:187], v[90:93]
	v_mfma_f32_16x16x32_bf16 v[126:129], v[160:163], v[172:175], v[126:129]
	v_mfma_f32_16x16x32_bf16 v[118:121], v[160:163], v[176:179], v[118:121]
	s_cbranch_vccz .LBB0_642
.LBB0_647:
	s_add_i32 s14, s14, 2
	s_cmp_gt_u32 s14, 13
	s_cselect_b64 s[8:9], -1, 0
	s_and_b64 vcc, exec, s[8:9]
	v_lshl_add_u64 v[142:143], v[138:139], 0, v[0:1]
	v_lshl_add_u64 v[140:141], v[136:137], 0, v[0:1]
	s_waitcnt lgkmcnt(0)
	s_barrier
	s_waitcnt vmcnt(8)
	ds_write_b128 v134, v[2:5]
	ds_write_b128 v134, v[10:13] offset:20480
	ds_write_b128 v134, v[18:21] offset:5120
	ds_write_b128 v134, v[26:29] offset:25600
	ds_write_b128 v134, v[34:37] offset:10240
	ds_write_b128 v134, v[42:45] offset:30720
	ds_write_b128 v134, v[50:53] offset:15360
	ds_write_b128 v134, v[58:61] offset:35840
	s_waitcnt lgkmcnt(0)
	s_barrier
	s_cbranch_vccnz .Lgw_skip_3
	global_load_dwordx4 v[2:5], v[188:189], off offset:256
	global_load_dwordx4 v[10:13], v[190:191], off offset:256
	global_load_dwordx4 v[18:21], v[192:193], off offset:256
	global_load_dwordx4 v[26:29], v[236:237], off offset:256
	global_load_dwordx4 v[34:37], v[240:241], off offset:256
	global_load_dwordx4 v[42:45], v[242:243], off offset:256
	global_load_dwordx4 v[50:53], v[244:245], off offset:256
	global_load_dwordx4 v[58:61], v[246:247], off offset:256
; DEV f32x4 mfma16(bf16x8 a, bf16x8 b, f32x4 c) { return __builtin_amdgcn_mfma_f32_16x16x32_bf16(a, b, c, 0, 0, 0); }
; #define G_LOAD(RA, RB, KT) { _Pragma("unroll") for (int i = 0; i < 4; i++) { \
;       RA[i] = *(const u32x4*)(Ap + (size_t)(i * 32) * lda + (KT) * 64); RB[i] = *(const u32x4*)(Bp + (size_t)(i * 32) * ldb + (KT) * 64); } }
; #define G_STORE(RA, RB) { _Pragma("unroll") for (int i = 0; i < 4; i++) { \
;       *(u32x4*)(As + (lrow + i * 32) * GLD + lcc * 8) = RA[i]; *(u32x4*)(Bs + (lrow + i * 32) * GLD + lcc * 8) = RB[i]; } }
; template <int TI, int TJ, int KS>
; DEV void mfma_lds(const bf16_t* Arows, int lda, const bf16_t* Brows, int ldb, int i0, int j0, f32x4 (&acc)[TI][TJ]) {
;     ...
;   for (int ks = 0; ks < KS; ks++) {
;     bf16x8 af[TI], bfr[TJ];
; #pragma unroll
;     for (int i = 0; i < TI; i++) af[i] = *(const bf16x8*)(Arows + (i0 + i * 16 + l15) * lda + ks * 32 + quad * 8);
; #pragma unroll
;     for (int j = 0; j < TJ; j++) bfr[j] = *(const bf16x8*)(Brows + (j0 + j * 16 + l15) * ldb + ks * 32 + quad * 8);
; #pragma unroll
;     for (int i = 0; i < TI; i++)
; #pragma unroll
;       for (int j = 0; j < TJ; j++) acc[i][j] = mfma16(af[i], bfr[j], acc[i][j]);
;   }
; template <class Epi>
; DEV void gemm_tile(const bf16_t* __restrict__ A, int lda, const bf16_t* __restrict__ Bt, int ldb, int K, int m0, int n0,
;                    Epi& epi, char* smem) {
;     ...
;     mfma_lds<4, 4, 2>(Bs, GLD, As, GLD, wn * 64, wm * 64, acc);
;     __syncthreads();
;     G_STORE(ra1, rb1);
;     __syncthreads();
;     if (kt + 3 < nk) G_LOAD(ra1, rb1, kt + 3);
.LBB0_649:
	v_mov_b32_e32 v130, v195
	s_cmp_gt_u32 s14, 12
	v_and_b32_e32 v135, 15, v130
	v_or_b32_e32 v131, v135, v144
	v_and_b32_e32 v148, 48, v130
	v_mul_u32_u24_e32 v130, 0x50, v131
	v_lshl_add_u32 v147, v130, 1, v148
	v_or_b32_e32 v135, v135, v146
	v_mad_u32_u24 v238, v135, s36, v148
	ds_read_b128 v[148:151], v147 offset:20480
	ds_read_b128 v[164:167], v238
	ds_read_b128 v[168:171], v238 offset:2560
	ds_read_b128 v[172:175], v238 offset:5120
	ds_read_b128 v[176:179], v238 offset:7680
	ds_read_b128 v[152:155], v147 offset:23040
	ds_read_b128 v[156:159], v147 offset:25600
	ds_read_b128 v[160:163], v147 offset:28160
	ds_read_b128 v[180:183], v238 offset:64
	ds_read_b128 v[184:187], v238 offset:2624
	s_waitcnt lgkmcnt(8)
	v_mfma_f32_16x16x32_bf16 v[106:109], v[148:151], v[164:167], v[106:109]
	s_waitcnt lgkmcnt(7)
	v_mfma_f32_16x16x32_bf16 v[122:125], v[148:151], v[168:171], v[122:125]
	s_waitcnt lgkmcnt(6)
	v_mfma_f32_16x16x32_bf16 v[114:117], v[148:151], v[172:175], v[114:117]
	s_waitcnt lgkmcnt(5)
	v_mfma_f32_16x16x32_bf16 v[110:113], v[148:151], v[176:179], v[110:113]
	ds_read_b128 v[148:151], v147 offset:20544
	s_waitcnt lgkmcnt(5)
	v_mfma_f32_16x16x32_bf16 v[102:105], v[152:155], v[164:167], v[102:105]
	v_mfma_f32_16x16x32_bf16 v[94:97], v[152:155], v[168:171], v[94:97]
	v_mfma_f32_16x16x32_bf16 v[86:89], v[152:155], v[172:175], v[86:89]
	v_mfma_f32_16x16x32_bf16 v[78:81], v[152:155], v[176:179], v[78:81]
	ds_read_b128 v[152:155], v147 offset:23104
	s_waitcnt lgkmcnt(5)
	v_mfma_f32_16x16x32_bf16 v[82:85], v[156:159], v[164:167], v[82:85]
	v_mfma_f32_16x16x32_bf16 v[74:77], v[156:159], v[168:171], v[74:77]
	v_mfma_f32_16x16x32_bf16 v[70:73], v[156:159], v[172:175], v[70:73]
	v_mfma_f32_16x16x32_bf16 v[66:69], v[156:159], v[176:179], v[66:69]
	ds_read_b128 v[156:159], v147 offset:25664
	s_waitcnt lgkmcnt(5)
	v_mfma_f32_16x16x32_bf16 v[126:129], v[160:163], v[172:175], v[126:129]
	v_mfma_f32_16x16x32_bf16 v[118:121], v[160:163], v[176:179], v[118:121]
	ds_read_b128 v[172:175], v238 offset:5184
	ds_read_b128 v[176:179], v238 offset:7744
	v_mfma_f32_16x16x32_bf16 v[98:101], v[160:163], v[164:167], v[98:101]
	v_mfma_f32_16x16x32_bf16 v[90:93], v[160:163], v[168:171], v[90:93]
	ds_read_b128 v[160:163], v147 offset:28224
	s_waitcnt lgkmcnt(5)
	v_mfma_f32_16x16x32_bf16 v[106:109], v[148:151], v[180:183], v[106:109]
	s_waitcnt lgkmcnt(4)
	v_mfma_f32_16x16x32_bf16 v[102:105], v[152:155], v[180:183], v[102:105]
	s_waitcnt lgkmcnt(3)
	v_mfma_f32_16x16x32_bf16 v[82:85], v[156:159], v[180:183], v[82:85]
	v_mfma_f32_16x16x32_bf16 v[122:125], v[148:151], v[184:187], v[122:125]
	v_mfma_f32_16x16x32_bf16 v[94:97], v[152:155], v[184:187], v[94:97]
	v_mfma_f32_16x16x32_bf16 v[74:77], v[156:159], v[184:187], v[74:77]
	s_waitcnt lgkmcnt(2)
	v_mfma_f32_16x16x32_bf16 v[114:117], v[148:151], v[172:175], v[114:117]
	v_mfma_f32_16x16x32_bf16 v[86:89], v[152:155], v[172:175], v[86:89]
	v_mfma_f32_16x16x32_bf16 v[70:73], v[156:159], v[172:175], v[70:73]
	s_waitcnt lgkmcnt(1)
	v_mfma_f32_16x16x32_bf16 v[110:113], v[148:151], v[176:179], v[110:113]
	v_mfma_f32_16x16x32_bf16 v[78:81], v[152:155], v[176:179], v[78:81]
	v_mfma_f32_16x16x32_bf16 v[66:69], v[156:159], v[176:179], v[66:69]
	s_waitcnt lgkmcnt(0)
	v_mfma_f32_16x16x32_bf16 v[98:101], v[160:163], v[180:183], v[98:101]
	s_barrier
	v_mfma_f32_16x16x32_bf16 v[90:93], v[160:163], v[184:187], v[90:93]
	s_waitcnt vmcnt(8)
	ds_write_b128 v134, v[6:9]
	ds_write_b128 v134, v[14:17] offset:20480
	ds_write_b128 v134, v[22:25] offset:5120
	ds_write_b128 v134, v[30:33] offset:25600
	ds_write_b128 v134, v[38:41] offset:10240
	ds_write_b128 v134, v[46:49] offset:30720
	ds_write_b128 v134, v[54:57] offset:15360
	ds_write_b128 v134, v[62:65] offset:35840
	v_mfma_f32_16x16x32_bf16 v[126:129], v[160:163], v[172:175], v[126:129]
	s_waitcnt lgkmcnt(0)
	s_barrier
	v_mfma_f32_16x16x32_bf16 v[118:121], v[160:163], v[176:179], v[118:121]
	s_cbranch_scc1 .LBB0_646
	global_load_dwordx4 v[6:9], v[188:189], off offset:384
	global_load_dwordx4 v[14:17], v[190:191], off offset:384
	global_load_dwordx4 v[22:25], v[192:193], off offset:384
	global_load_dwordx4 v[30:33], v[236:237], off offset:384
	global_load_dwordx4 v[38:41], v[240:241], off offset:384
	global_load_dwordx4 v[46:49], v[242:243], off offset:384
	global_load_dwordx4 v[54:57], v[244:245], off offset:384
	global_load_dwordx4 v[62:65], v[246:247], off offset:384
	s_branch .LBB0_646

; DEV int tidx() { int t = threadIdx.x; asm volatile("" : "+v"(t)); return t; }
; #define G_LOAD(RA, RB, KT) { _Pragma("unroll") for (int i = 0; i < 4; i++) { \
;       RA[i] = *(const u32x4*)(Ap + (size_t)(i * 32) * lda + (KT) * 64); RB[i] = *(const u32x4*)(Bp + (size_t)(i * 32) * ldb + (KT) * 64); } }
; template <class Epi>
; DEV void gemm_tile(const bf16_t* __restrict__ A, int lda, const bf16_t* __restrict__ Bt, int ldb, int K, int m0, int n0,
;                    Epi& epi, char* smem) {
;   bf16_t* As = (bf16_t*)smem;
;   bf16_t* Bs = As + 128 * GLD;
;   const int tid = tidx(), lane = tid & 63, w = tid >> 6, wm = w >> 1, wn = w & 1;
;   const int l15 = lane & 15, quad = lane >> 4;
;   f32x4 acc[4][4];
; #pragma unroll
;   for (int i = 0; i < 4; i++)
; #pragma unroll
;     for (int j = 0; j < 4; j++) acc[i][j] = (f32x4){0.f, 0.f, 0.f, 0.f};
;   u32x4 ra0[4], rb0[4], ra1[4], rb1[4];
;   const int nk = K >> 6;
;   const int lrow = tid >> 3, lcc = tid & 7;
;   const bf16_t* Ap = A + (size_t)(m0 + lrow) * lda + lcc * 8;
;   const bf16_t* Bp = Bt + (size_t)(n0 + lrow) * ldb + lcc * 8;
;     ...
;   G_LOAD(ra0, rb0, 0);
;   G_LOAD(ra1, rb1, 1);
.LBB0_668:
	s_ashr_i32 s8, s12, 6
	s_and_b32 s9, s12, 7
	s_and_b32 s13, s8, 0x1ffffff8
	s_or_b32 s9, s13, s9
	s_lshl_b32 s9, s9, 3
	s_bfe_u32 s13, s12, 0x30006
	s_or_b32 s9, s9, s13
	s_cmpk_gt_i32 s9, 0x83
	s_cbranch_scc1 .LBB0_667
	s_bfe_u32 s14, s11, 0x30007
	s_mul_i32 s15, s14, 0x44000
	s_and_b32 s14, s10, 7
	v_mov_b32_e32 v141, v195
	s_lshl_b32 s18, s14, 3
	s_lshl_b32 s14, s9, 7
	s_movk_i32 s20, 0x880
	v_ashrrev_i32_e32 v2, 3, v141
	v_add_u32_e32 v0, s14, v2
	v_mov_b64_e32 v[4:5], s[6:7]
	s_lshr_b32 s13, s12, 6
	s_lshl_b32 s9, s12, 4
	v_mad_i64_i32 v[4:5], s[16:17], v0, s20, v[4:5]
	v_lshlrev_b32_e32 v0, 4, v141
	s_and_b32 s19, s13, 7
	s_and_b32 s13, s9, 0x380
	v_and_b32_e32 v0, 0x70, v0
	v_lshl_add_u64 v[4:5], v[4:5], 0, v[0:1]
	v_add_u32_e32 v3, s13, v2
	v_mov_b64_e32 v[6:7], s[2:3]
	s_mov_b32 s9, 0x11000
	v_mad_i64_i32 v[6:7], s[16:17], v3, s20, v[6:7]
	v_add_co_u32_e32 v8, vcc, s9, v4
	v_lshl_add_u64 v[6:7], v[6:7], 0, v[0:1]
	s_nop 0
	v_addc_co_u32_e32 v9, vcc, 0, v5, vcc
	v_add_co_u32_e32 v10, vcc, s9, v6
	s_mov_b32 s9, 0x22000
	s_nop 0
	v_addc_co_u32_e32 v11, vcc, 0, v7, vcc
	v_add_co_u32_e32 v12, vcc, s9, v4
	v_mad_u64_u32 v[130:131], s[16:17], v2, s36, v[0:1]
	s_nop 0
	v_addc_co_u32_e32 v13, vcc, 0, v5, vcc
	s_waitcnt vmcnt(22)
	v_add_co_u32_e32 v14, vcc, s9, v6
	s_mov_b32 s9, 0x33000
	s_nop 0
	v_addc_co_u32_e32 v15, vcc, 0, v7, vcc
	v_add_co_u32_e32 v16, vcc, s9, v4
	s_add_u32 s16, s28, s15
	s_nop 0
	v_addc_co_u32_e32 v17, vcc, 0, v5, vcc
	v_add_co_u32_e32 v18, vcc, s9, v6
	s_addc_u32 s17, s29, 0
	s_nop 0
	v_addc_co_u32_e32 v19, vcc, 0, v7, vcc
	global_load_dwordx4 v[42:45], v[4:5], off
	global_load_dwordx4 v[50:53], v[6:7], off
	global_load_dwordx4 v[62:65], v[8:9], off
	global_load_dwordx4 v[70:73], v[10:11], off
	global_load_dwordx4 v[78:81], v[12:13], off
	global_load_dwordx4 v[86:89], v[14:15], off
	global_load_dwordx4 v[94:97], v[16:17], off
	global_load_dwordx4 v[102:105], v[18:19], off
	v_mov_b64_e32 v[188:189], v[4:5]
	v_mov_b64_e32 v[190:191], v[6:7]
	v_mov_b64_e32 v[192:193], v[8:9]
	v_mov_b64_e32 v[236:237], v[10:11]
	v_mov_b64_e32 v[240:241], v[12:13]
	v_mov_b64_e32 v[242:243], v[14:15]
	v_mov_b64_e32 v[244:245], v[16:17]
	v_mov_b64_e32 v[246:247], v[18:19]
	global_load_dwordx4 v[46:49], v[4:5], off offset:128
	global_load_dwordx4 v[54:57], v[6:7], off offset:128
	global_load_dwordx4 v[66:69], v[8:9], off offset:128
	global_load_dwordx4 v[74:77], v[10:11], off offset:128
	global_load_dwordx4 v[82:85], v[12:13], off offset:128
	global_load_dwordx4 v[90:93], v[14:15], off offset:128
	global_load_dwordx4 v[98:101], v[16:17], off offset:128
	global_load_dwordx4 v[106:109], v[18:19], off offset:128
	s_lshl_b32 s8, s8, 3
	s_and_b32 s8, s8, 0x1ffffc0
	s_or_b32 s8, s8, s18
	s_or_b32 s8, s8, s19
	v_ashrrev_i32_e32 v3, 1, v141
	s_lshl_b32 s8, s8, 7
	v_and_b32_e32 v142, 0xffffffc0, v3
	v_ashrrev_i32_e32 v3, 31, v2
	v_mov_b64_e32 v[4:5], s[16:17]
	s_ashr_i32 s9, s8, 31
	v_mad_i64_i32 v[132:133], s[16:17], v2, s20, v[4:5]
	s_movk_i32 s19, 0x880
	v_lshl_add_u64 v[2:3], v[2:3], 0, s[8:9]
	v_mov_b64_e32 v[4:5], s[28:29]
	v_and_b32_e32 v0, 7, v141
	v_mad_u64_u32 v[134:135], s[8:9], v2, s19, v[4:5]
	v_mov_b32_e32 v2, 0
	v_and_b32_e32 v140, 64, v141
	v_lshlrev_b32_e32 v0, 4, v0
	v_mad_i32_i24 v135, v3, s19, v135
	s_mov_b32 s15, -2
	v_mov_b32_e32 v3, v2
	v_mov_b32_e32 v4, v2
	v_mov_b32_e32 v5, v2
	v_mov_b32_e32 v6, v2
	v_mov_b32_e32 v7, v2
	v_mov_b32_e32 v8, v2
	v_mov_b32_e32 v9, v2
	v_mov_b32_e32 v10, v2
	v_mov_b32_e32 v11, v2
	v_mov_b32_e32 v12, v2
	v_mov_b32_e32 v13, v2
	v_mov_b32_e32 v14, v2
	v_mov_b32_e32 v15, v2
	v_mov_b32_e32 v16, v2
	v_mov_b32_e32 v17, v2
	v_mov_b32_e32 v18, v2
	v_mov_b32_e32 v19, v2
	v_mov_b32_e32 v20, v2
	v_mov_b32_e32 v21, v2
	s_waitcnt vmcnt(37)
	v_mov_b32_e32 v22, v2
	v_mov_b32_e32 v23, v2
	v_mov_b32_e32 v24, v2
	v_mov_b32_e32 v25, v2
	v_mov_b32_e32 v26, v2
	v_mov_b32_e32 v27, v2
	v_mov_b32_e32 v28, v2
	v_mov_b32_e32 v29, v2
	s_waitcnt vmcnt(36)
	v_mov_b32_e32 v30, v2
	v_mov_b32_e32 v31, v2
	v_mov_b32_e32 v32, v2
	v_mov_b32_e32 v33, v2
	v_mov_b32_e32 v34, v2
	v_mov_b32_e32 v35, v2
	v_mov_b32_e32 v36, v2
	v_mov_b32_e32 v37, v2
	s_waitcnt vmcnt(35)
	v_mov_b32_e32 v38, v2
	v_mov_b32_e32 v39, v2
	v_mov_b32_e32 v40, v2
	v_mov_b32_e32 v41, v2
	v_mov_b32_e32 v58, v2
	v_mov_b32_e32 v59, v2
	v_mov_b32_e32 v60, v2
	v_mov_b32_e32 v61, v2
	s_waitcnt vmcnt(34)
	v_mov_b32_e32 v110, v2
	v_mov_b32_e32 v111, v2
	v_mov_b32_e32 v112, v2
	v_mov_b32_e32 v113, v2
	v_mov_b32_e32 v114, v2
	v_mov_b32_e32 v115, v2
	v_mov_b32_e32 v116, v2
	v_mov_b32_e32 v117, v2
	s_waitcnt vmcnt(33)
	v_mov_b32_e32 v118, v2
	v_mov_b32_e32 v119, v2
	v_mov_b32_e32 v120, v2
	v_mov_b32_e32 v121, v2
	v_mov_b32_e32 v122, v2
	v_mov_b32_e32 v123, v2
	v_mov_b32_e32 v124, v2
	v_mov_b32_e32 v125, v2
	s_waitcnt vmcnt(32)
	v_mov_b32_e32 v126, v2
	v_mov_b32_e32 v127, v2
	v_mov_b32_e32 v128, v2
	v_mov_b32_e32 v129, v2
	s_branch .LBB0_671
; DEV f32x4 mfma16(bf16x8 a, bf16x8 b, f32x4 c) { return __builtin_amdgcn_mfma_f32_16x16x32_bf16(a, b, c, 0, 0, 0); }
; #define G_LOAD(RA, RB, KT) { _Pragma("unroll") for (int i = 0; i < 4; i++) { \
;       RA[i] = *(const u32x4*)(Ap + (size_t)(i * 32) * lda + (KT) * 64); RB[i] = *(const u32x4*)(Bp + (size_t)(i * 32) * ldb + (KT) * 64); } }
; #define G_STORE(RA, RB) { _Pragma("unroll") for (int i = 0; i < 4; i++) { \
;       *(u32x4*)(As + (lrow + i * 32) * GLD + lcc * 8) = RA[i]; *(u32x4*)(Bs + (lrow + i * 32) * GLD + lcc * 8) = RB[i]; } }
; template <int TI, int TJ, int KS>
; DEV void mfma_lds(const bf16_t* Arows, int lda, const bf16_t* Brows, int ldb, int i0, int j0, f32x4 (&acc)[TI][TJ]) {
;     ...
;   for (int ks = 0; ks < KS; ks++) {
;     bf16x8 af[TI], bfr[TJ];
; #pragma unroll
;     for (int i = 0; i < TI; i++) af[i] = *(const bf16x8*)(Arows + (i0 + i * 16 + l15) * lda + ks * 32 + quad * 8);
; #pragma unroll
;     for (int j = 0; j < TJ; j++) bfr[j] = *(const bf16x8*)(Brows + (j0 + j * 16 + l15) * ldb + ks * 32 + quad * 8);
; #pragma unroll
;     for (int i = 0; i < TI; i++)
; #pragma unroll
;       for (int j = 0; j < TJ; j++) acc[i][j] = mfma16(af[i], bfr[j], acc[i][j]);
;   }
; template <class Epi>
; DEV void gemm_tile(const bf16_t* __restrict__ A, int lda, const bf16_t* __restrict__ Bt, int ldb, int K, int m0, int n0,
;                    Epi& epi, char* smem) {
;     ...
;   for (int kt = 0; kt < nk; kt += 2) {
;     __syncthreads();
;     G_STORE(ra0, rb0);
;     __syncthreads();
;     if (kt + 2 < nk) G_LOAD(ra0, rb0, kt + 2);
;     mfma_lds<4, 4, 2>(Bs, GLD, As, GLD, wn * 64, wm * 64, acc);
;     __syncthreads();
;     G_STORE(ra1, rb1);
;     __syncthreads();
;     if (kt + 3 < nk) G_LOAD(ra1, rb1, kt + 3);
;     mfma_lds<4, 4, 2>(Bs, GLD, As, GLD, wn * 64, wm * 64, acc);
.LBB0_670:
	v_mov_b32_e32 v131, v195
	v_and_b32_e32 v143, 15, v131
	v_or_b32_e32 v144, v143, v140
	v_and_b32_e32 v148, 48, v131
	v_mul_u32_u24_e32 v131, 0x50, v144
	v_lshl_add_u32 v131, v131, 1, v148
	v_or_b32_e32 v143, v143, v142
	v_mad_u32_u24 v238, v143, s36, v148
	v_lshl_add_u64 v[132:133], v[132:133], 0, s[34:35]
	v_lshl_add_u64 v[134:135], v[134:135], 0, s[34:35]
	s_and_b64 vcc, exec, s[8:9]
	ds_read_b128 v[144:147], v131 offset:20480
	ds_read_b128 v[160:163], v238
	ds_read_b128 v[164:167], v238 offset:2560
	ds_read_b128 v[168:171], v238 offset:5120
	ds_read_b128 v[172:175], v238 offset:7680
	ds_read_b128 v[148:151], v131 offset:23040
	ds_read_b128 v[152:155], v131 offset:25600
	ds_read_b128 v[156:159], v131 offset:28160
	ds_read_b128 v[176:179], v238 offset:64
	ds_read_b128 v[180:183], v238 offset:2624
	v_lshl_add_u64 v[188:189], v[188:189], 0, s[34:35]
	v_lshl_add_u64 v[190:191], v[190:191], 0, s[34:35]
	v_lshl_add_u64 v[192:193], v[192:193], 0, s[34:35]
	v_lshl_add_u64 v[236:237], v[236:237], 0, s[34:35]
	v_lshl_add_u64 v[240:241], v[240:241], 0, s[34:35]
	v_lshl_add_u64 v[242:243], v[242:243], 0, s[34:35]
	v_lshl_add_u64 v[244:245], v[244:245], 0, s[34:35]
	v_lshl_add_u64 v[246:247], v[246:247], 0, s[34:35]
	s_waitcnt lgkmcnt(8)
	v_mfma_f32_16x16x32_bf16 v[126:129], v[144:147], v[160:163], v[126:129]
	s_waitcnt lgkmcnt(7)
	v_mfma_f32_16x16x32_bf16 v[122:125], v[144:147], v[164:167], v[122:125]
	s_waitcnt lgkmcnt(6)
	v_mfma_f32_16x16x32_bf16 v[118:121], v[144:147], v[168:171], v[118:121]
	s_waitcnt lgkmcnt(5)
	v_mfma_f32_16x16x32_bf16 v[114:117], v[144:147], v[172:175], v[114:117]
	ds_read_b128 v[144:147], v131 offset:20544
	s_waitcnt lgkmcnt(5)
	v_mfma_f32_16x16x32_bf16 v[110:113], v[148:151], v[160:163], v[110:113]
	v_mfma_f32_16x16x32_bf16 v[58:61], v[148:151], v[164:167], v[58:61]
	v_mfma_f32_16x16x32_bf16 v[38:41], v[148:151], v[168:171], v[38:41]
	v_mfma_f32_16x16x32_bf16 v[34:37], v[148:151], v[172:175], v[34:37]
	ds_read_b128 v[148:151], v131 offset:23104
	s_waitcnt lgkmcnt(5)
	v_mfma_f32_16x16x32_bf16 v[30:33], v[152:155], v[160:163], v[30:33]
	v_mfma_f32_16x16x32_bf16 v[26:29], v[152:155], v[164:167], v[26:29]
	v_mfma_f32_16x16x32_bf16 v[22:25], v[152:155], v[168:171], v[22:25]
	v_mfma_f32_16x16x32_bf16 v[18:21], v[152:155], v[172:175], v[18:21]
	ds_read_b128 v[152:155], v131 offset:25664
	s_waitcnt lgkmcnt(5)
	v_mfma_f32_16x16x32_bf16 v[6:9], v[156:159], v[168:171], v[6:9]
	v_mfma_f32_16x16x32_bf16 v[2:5], v[156:159], v[172:175], v[2:5]
	ds_read_b128 v[168:171], v238 offset:5184
	ds_read_b128 v[172:175], v238 offset:7744
	v_mfma_f32_16x16x32_bf16 v[14:17], v[156:159], v[160:163], v[14:17]
	v_mfma_f32_16x16x32_bf16 v[10:13], v[156:159], v[164:167], v[10:13]
	ds_read_b128 v[156:159], v131 offset:28224
	s_waitcnt lgkmcnt(5)
	v_mfma_f32_16x16x32_bf16 v[126:129], v[144:147], v[176:179], v[126:129]
	s_waitcnt lgkmcnt(4)
	v_mfma_f32_16x16x32_bf16 v[110:113], v[148:151], v[176:179], v[110:113]
	s_waitcnt lgkmcnt(3)
	v_mfma_f32_16x16x32_bf16 v[30:33], v[152:155], v[176:179], v[30:33]
	v_mfma_f32_16x16x32_bf16 v[122:125], v[144:147], v[180:183], v[122:125]
	v_mfma_f32_16x16x32_bf16 v[58:61], v[148:151], v[180:183], v[58:61]
	v_mfma_f32_16x16x32_bf16 v[26:29], v[152:155], v[180:183], v[26:29]
	s_waitcnt lgkmcnt(2)
	v_mfma_f32_16x16x32_bf16 v[118:121], v[144:147], v[168:171], v[118:121]
	v_mfma_f32_16x16x32_bf16 v[38:41], v[148:151], v[168:171], v[38:41]
	v_mfma_f32_16x16x32_bf16 v[22:25], v[152:155], v[168:171], v[22:25]
	s_waitcnt lgkmcnt(1)
	v_mfma_f32_16x16x32_bf16 v[114:117], v[144:147], v[172:175], v[114:117]
	v_mfma_f32_16x16x32_bf16 v[34:37], v[148:151], v[172:175], v[34:37]
	v_mfma_f32_16x16x32_bf16 v[18:21], v[152:155], v[172:175], v[18:21]
	s_waitcnt lgkmcnt(0)
	v_mfma_f32_16x16x32_bf16 v[14:17], v[156:159], v[176:179], v[14:17]
	v_mfma_f32_16x16x32_bf16 v[10:13], v[156:159], v[180:183], v[10:13]
	v_mfma_f32_16x16x32_bf16 v[6:9], v[156:159], v[168:171], v[6:9]
	v_mfma_f32_16x16x32_bf16 v[2:5], v[156:159], v[172:175], v[2:5]
	s_cbranch_vccnz .LBB0_675
.LBB0_671:
	s_add_i32 s15, s15, 2
	s_cmp_gt_u32 s15, 13
	s_cselect_b64 s[8:9], -1, 0
	s_and_b64 vcc, exec, s[8:9]
	v_lshl_add_u64 v[138:139], v[134:135], 0, v[0:1]
	v_lshl_add_u64 v[136:137], v[132:133], 0, v[0:1]
	s_waitcnt lgkmcnt(0)
	s_barrier
	s_waitcnt vmcnt(8)
	ds_write_b128 v130, v[42:45]
	ds_write_b128 v130, v[50:53] offset:20480
	ds_write_b128 v130, v[62:65] offset:5120
	ds_write_b128 v130, v[70:73] offset:25600
	ds_write_b128 v130, v[78:81] offset:10240
	ds_write_b128 v130, v[86:89] offset:30720
	ds_write_b128 v130, v[94:97] offset:15360
	ds_write_b128 v130, v[102:105] offset:35840
	s_waitcnt lgkmcnt(0)
	s_barrier
	s_cbranch_vccnz .Lgw_skip_4
	global_load_dwordx4 v[42:45], v[188:189], off offset:256
	global_load_dwordx4 v[50:53], v[190:191], off offset:256
	global_load_dwordx4 v[62:65], v[192:193], off offset:256
	global_load_dwordx4 v[70:73], v[236:237], off offset:256
	global_load_dwordx4 v[78:81], v[240:241], off offset:256
	global_load_dwordx4 v[86:89], v[242:243], off offset:256
	global_load_dwordx4 v[94:97], v[244:245], off offset:256
	global_load_dwordx4 v[102:105], v[246:247], off offset:256
; DEV f32x4 mfma16(bf16x8 a, bf16x8 b, f32x4 c) { return __builtin_amdgcn_mfma_f32_16x16x32_bf16(a, b, c, 0, 0, 0); }
; #define G_LOAD(RA, RB, KT) { _Pragma("unroll") for (int i = 0; i < 4; i++) { \
;       RA[i] = *(const u32x4*)(Ap + (size_t)(i * 32) * lda + (KT) * 64); RB[i] = *(const u32x4*)(Bp + (size_t)(i * 32) * ldb + (KT) * 64); } }
; #define G_STORE(RA, RB) { _Pragma("unroll") for (int i = 0; i < 4; i++) { \
;       *(u32x4*)(As + (lrow + i * 32) * GLD + lcc * 8) = RA[i]; *(u32x4*)(Bs + (lrow + i * 32) * GLD + lcc * 8) = RB[i]; } }
; template <int TI, int TJ, int KS>
; DEV void mfma_lds(const bf16_t* Arows, int lda, const bf16_t* Brows, int ldb, int i0, int j0, f32x4 (&acc)[TI][TJ]) {
;     ...
;   for (int ks = 0; ks < KS; ks++) {
;     bf16x8 af[TI], bfr[TJ];
; #pragma unroll
;     for (int i = 0; i < TI; i++) af[i] = *(const bf16x8*)(Arows + (i0 + i * 16 + l15) * lda + ks * 32 + quad * 8);
; #pragma unroll
;     for (int j = 0; j < TJ; j++) bfr[j] = *(const bf16x8*)(Brows + (j0 + j * 16 + l15) * ldb + ks * 32 + quad * 8);
; #pragma unroll
;     for (int i = 0; i < TI; i++)
; #pragma unroll
;       for (int j = 0; j < TJ; j++) acc[i][j] = mfma16(af[i], bfr[j], acc[i][j]);
;   }
; template <class Epi>
; DEV void gemm_tile(const bf16_t* __restrict__ A, int lda, const bf16_t* __restrict__ Bt, int ldb, int K, int m0, int n0,
;                    Epi& epi, char* smem) {
;     ...
;     mfma_lds<4, 4, 2>(Bs, GLD, As, GLD, wn * 64, wm * 64, acc);
;     __syncthreads();
;     G_STORE(ra1, rb1);
;     __syncthreads();
;     if (kt + 3 < nk) G_LOAD(ra1, rb1, kt + 3);
.LBB0_673:
	v_mov_b32_e32 v131, v195
	s_cmp_gt_u32 s15, 12
	v_and_b32_e32 v143, 15, v131
	v_or_b32_e32 v144, v143, v140
	v_and_b32_e32 v148, 48, v131
	v_mul_u32_u24_e32 v131, 0x50, v144
	v_lshl_add_u32 v131, v131, 1, v148
	v_or_b32_e32 v143, v143, v142
	v_mad_u32_u24 v238, v143, s36, v148
	ds_read_b128 v[144:147], v131 offset:20480
	ds_read_b128 v[160:163], v238
	ds_read_b128 v[164:167], v238 offset:2560
	ds_read_b128 v[168:171], v238 offset:5120
	ds_read_b128 v[172:175], v238 offset:7680
	ds_read_b128 v[148:151], v131 offset:23040
	ds_read_b128 v[152:155], v131 offset:25600
	ds_read_b128 v[156:159], v131 offset:28160
	ds_read_b128 v[176:179], v238 offset:64
	ds_read_b128 v[180:183], v238 offset:2624
	s_waitcnt lgkmcnt(8)
	v_mfma_f32_16x16x32_bf16 v[126:129], v[144:147], v[160:163], v[126:129]
	s_waitcnt lgkmcnt(7)
	v_mfma_f32_16x16x32_bf16 v[122:125], v[144:147], v[164:167], v[122:125]
	s_waitcnt lgkmcnt(6)
	v_mfma_f32_16x16x32_bf16 v[118:121], v[144:147], v[168:171], v[118:121]
	s_waitcnt lgkmcnt(5)
	v_mfma_f32_16x16x32_bf16 v[114:117], v[144:147], v[172:175], v[114:117]
	ds_read_b128 v[144:147], v131 offset:20544
	s_waitcnt lgkmcnt(5)
	v_mfma_f32_16x16x32_bf16 v[110:113], v[148:151], v[160:163], v[110:113]
	v_mfma_f32_16x16x32_bf16 v[58:61], v[148:151], v[164:167], v[58:61]
	v_mfma_f32_16x16x32_bf16 v[38:41], v[148:151], v[168:171], v[38:41]
	v_mfma_f32_16x16x32_bf16 v[34:37], v[148:151], v[172:175], v[34:37]
	ds_read_b128 v[148:151], v131 offset:23104
	s_waitcnt lgkmcnt(5)
	v_mfma_f32_16x16x32_bf16 v[30:33], v[152:155], v[160:163], v[30:33]
	v_mfma_f32_16x16x32_bf16 v[26:29], v[152:155], v[164:167], v[26:29]
	v_mfma_f32_16x16x32_bf16 v[22:25], v[152:155], v[168:171], v[22:25]
	v_mfma_f32_16x16x32_bf16 v[18:21], v[152:155], v[172:175], v[18:21]
	ds_read_b128 v[152:155], v131 offset:25664
	s_waitcnt lgkmcnt(5)
	v_mfma_f32_16x16x32_bf16 v[6:9], v[156:159], v[168:171], v[6:9]
	v_mfma_f32_16x16x32_bf16 v[2:5], v[156:159], v[172:175], v[2:5]
	ds_read_b128 v[168:171], v238 offset:5184
	ds_read_b128 v[172:175], v238 offset:7744
	v_mfma_f32_16x16x32_bf16 v[14:17], v[156:159], v[160:163], v[14:17]
	v_mfma_f32_16x16x32_bf16 v[10:13], v[156:159], v[164:167], v[10:13]
	ds_read_b128 v[156:159], v131 offset:28224
	s_waitcnt lgkmcnt(5)
	v_mfma_f32_16x16x32_bf16 v[126:129], v[144:147], v[176:179], v[126:129]
	s_waitcnt lgkmcnt(4)
	v_mfma_f32_16x16x32_bf16 v[110:113], v[148:151], v[176:179], v[110:113]
	s_waitcnt lgkmcnt(3)
	v_mfma_f32_16x16x32_bf16 v[30:33], v[152:155], v[176:179], v[30:33]
	v_mfma_f32_16x16x32_bf16 v[122:125], v[144:147], v[180:183], v[122:125]
	v_mfma_f32_16x16x32_bf16 v[58:61], v[148:151], v[180:183], v[58:61]
	v_mfma_f32_16x16x32_bf16 v[26:29], v[152:155], v[180:183], v[26:29]
	s_waitcnt lgkmcnt(2)
	v_mfma_f32_16x16x32_bf16 v[118:121], v[144:147], v[168:171], v[118:121]
	v_mfma_f32_16x16x32_bf16 v[38:41], v[148:151], v[168:171], v[38:41]
	v_mfma_f32_16x16x32_bf16 v[22:25], v[152:155], v[168:171], v[22:25]
	s_waitcnt lgkmcnt(1)
	v_mfma_f32_16x16x32_bf16 v[114:117], v[144:147], v[172:175], v[114:117]
	v_mfma_f32_16x16x32_bf16 v[34:37], v[148:151], v[172:175], v[34:37]
	v_mfma_f32_16x16x32_bf16 v[18:21], v[152:155], v[172:175], v[18:21]
	s_waitcnt lgkmcnt(0)
	v_mfma_f32_16x16x32_bf16 v[14:17], v[156:159], v[176:179], v[14:17]
	s_barrier
	v_mfma_f32_16x16x32_bf16 v[10:13], v[156:159], v[180:183], v[10:13]
	s_waitcnt vmcnt(8)
	ds_write_b128 v130, v[46:49]
	ds_write_b128 v130, v[54:57] offset:20480
	ds_write_b128 v130, v[66:69] offset:5120
	ds_write_b128 v130, v[74:77] offset:25600
	ds_write_b128 v130, v[82:85] offset:10240
	ds_write_b128 v130, v[90:93] offset:30720
	ds_write_b128 v130, v[98:101] offset:15360
	ds_write_b128 v130, v[106:109] offset:35840
	v_mfma_f32_16x16x32_bf16 v[6:9], v[156:159], v[168:171], v[6:9]
	s_waitcnt lgkmcnt(0)
	s_barrier
	v_mfma_f32_16x16x32_bf16 v[2:5], v[156:159], v[172:175], v[2:5]
	s_cbranch_scc1 .LBB0_670
	global_load_dwordx4 v[46:49], v[188:189], off offset:384
	global_load_dwordx4 v[54:57], v[190:191], off offset:384
	global_load_dwordx4 v[66:69], v[192:193], off offset:384
	global_load_dwordx4 v[74:77], v[236:237], off offset:384
	global_load_dwordx4 v[82:85], v[240:241], off offset:384
	global_load_dwordx4 v[90:93], v[242:243], off offset:384
	global_load_dwordx4 v[98:101], v[244:245], off offset:384
	global_load_dwordx4 v[106:109], v[246:247], off offset:384
	s_branch .LBB0_670

; DEV int tidx() { int t = threadIdx.x; asm volatile("" : "+v"(t)); return t; }
; #define G_LOAD(RA, RB, KT) { _Pragma("unroll") for (int i = 0; i < 4; i++) { \
;       RA[i] = *(const u32x4*)(Ap + (size_t)(i * 32) * lda + (KT) * 64); RB[i] = *(const u32x4*)(Bp + (size_t)(i * 32) * ldb + (KT) * 64); } }
; template <class Epi>
; DEV void gemm_tile(const bf16_t* __restrict__ A, int lda, const bf16_t* __restrict__ Bt, int ldb, int K, int m0, int n0,
;                    Epi& epi, char* smem) {
;     ...
;   const int tid = tidx(), lane = tid & 63, w = tid >> 6, wm = w >> 1, wn = w & 1;
;   const int l15 = lane & 15, quad = lane >> 4;
;   f32x4 acc[4][4];
; #pragma unroll
;   for (int i = 0; i < 4; i++)
; #pragma unroll
;     for (int j = 0; j < 4; j++) acc[i][j] = (f32x4){0.f, 0.f, 0.f, 0.f};
;   u32x4 ra0[4], rb0[4], ra1[4], rb1[4];
;   const int nk = K >> 6;
;   const int lrow = tid >> 3, lcc = tid & 7;
;   const bf16_t* Ap = A + (size_t)(m0 + lrow) * lda + lcc * 8;
;   const bf16_t* Bp = Bt + (size_t)(n0 + lrow) * ldb + lcc * 8;
;     ...
;   G_LOAD(ra0, rb0, 0);
;   G_LOAD(ra1, rb1, 1);
; DEV void phase_gemm_win(const Params& p, char* smem) {
;     ...
;   for (int item = blockIdx.x; item < items; item += gridDim.x) {
;     int mt = item / NTL, nt = item - mt * NTL;
;     gemm_tile(WSP(bf16_t, OFF_H), LDH, WSP(bf16_t, S_WIN0), LDH, 1024, mt * 128, nt * 128, epi, smem);
.LBB0_1037:
	s_mul_hi_i32 s8, s11, 0x2aaaaaab
	s_lshr_b32 s9, s8, 31
	s_ashr_i32 s8, s8, 1
	s_add_i32 s14, s8, s9
	v_mov_b32_e32 v140, v195
	s_mul_i32 s8, s14, -12
	s_lshl_b32 s12, s14, 7
	s_add_i32 s8, s8, s11
	v_ashrrev_i32_e32 v66, 3, v140
	v_add_u32_e32 v68, s12, v66
	v_mov_b64_e32 v[2:3], s[2:3]
	v_lshlrev_b32_e32 v0, 4, v140
	s_lshl_b32 s13, s8, 7
	v_mad_i64_i32 v[2:3], s[8:9], v68, s19, v[2:3]
	v_and_b32_e32 v0, 0x70, v0
	v_lshl_add_u64 v[6:7], v[2:3], 0, v[0:1]
	v_add_u32_e32 v4, s13, v66
	v_mov_b64_e32 v[2:3], s[6:7]
	v_mad_i64_i32 v[2:3], s[8:9], v4, s19, v[2:3]
	s_mov_b32 s8, 0x11000
	s_waitcnt vmcnt(5)
	v_add_co_u32_e32 v22, vcc, s8, v6
	v_lshl_add_u64 v[14:15], v[2:3], 0, v[0:1]
	s_nop 0
	v_addc_co_u32_e32 v23, vcc, 0, v7, vcc
	s_waitcnt vmcnt(4)
	v_add_co_u32_e32 v30, vcc, s8, v14
	s_mov_b32 s8, 0x22000
	s_nop 0
	v_addc_co_u32_e32 v31, vcc, 0, v15, vcc
	s_waitcnt vmcnt(3)
	v_add_co_u32_e32 v38, vcc, s8, v6
	v_ashrrev_i32_e32 v67, 1, v140
	s_nop 0
	v_addc_co_u32_e32 v39, vcc, 0, v7, vcc
	s_waitcnt vmcnt(2)
	v_add_co_u32_e32 v46, vcc, s8, v14
	s_mov_b32 s8, 0x33000
	s_nop 0
	v_addc_co_u32_e32 v47, vcc, 0, v15, vcc
	s_waitcnt vmcnt(1)
	v_add_co_u32_e32 v54, vcc, s8, v6
	s_mulk_i32 s14, 0x600
	s_nop 0
	v_addc_co_u32_e32 v55, vcc, 0, v7, vcc
	s_waitcnt vmcnt(0)
	v_add_co_u32_e32 v62, vcc, s8, v14
	v_mad_u64_u32 v[130:131], s[8:9], v66, s36, v[0:1]
	s_nop 0
	v_addc_co_u32_e32 v63, vcc, 0, v15, vcc
	global_load_dwordx4 v[2:5], v[6:7], off
	s_nop 0
	global_load_dwordx4 v[10:13], v[14:15], off
	s_nop 0
	global_load_dwordx4 v[18:21], v[22:23], off
	s_nop 0
	global_load_dwordx4 v[26:29], v[30:31], off
	s_nop 0
	global_load_dwordx4 v[34:37], v[38:39], off
	s_nop 0
	global_load_dwordx4 v[42:45], v[46:47], off
	s_nop 0
	global_load_dwordx4 v[50:53], v[54:55], off
	s_nop 0
	global_load_dwordx4 v[58:61], v[62:63], off
	s_nop 0
	v_mov_b64_e32 v[188:189], v[6:7]
	v_mov_b64_e32 v[190:191], v[14:15]
	v_mov_b64_e32 v[192:193], v[22:23]
	v_mov_b64_e32 v[236:237], v[30:31]
	v_mov_b64_e32 v[240:241], v[38:39]
	v_mov_b64_e32 v[242:243], v[46:47]
	v_mov_b64_e32 v[244:245], v[54:55]
	v_mov_b64_e32 v[246:247], v[62:63]
	global_load_dwordx4 v[6:9], v[6:7], off offset:128
	s_nop 0
	global_load_dwordx4 v[14:17], v[14:15], off offset:128
	s_nop 0
	global_load_dwordx4 v[22:25], v[22:23], off offset:128
	s_nop 0
	global_load_dwordx4 v[30:33], v[30:31], off offset:128
	s_nop 0
	global_load_dwordx4 v[38:41], v[38:39], off offset:128
	s_nop 0
	global_load_dwordx4 v[46:49], v[46:47], off offset:128
	s_nop 0
	global_load_dwordx4 v[54:57], v[54:55], off offset:128
	s_nop 0
	global_load_dwordx4 v[62:65], v[62:63], off offset:128
	v_add_u32_e32 v66, s10, v66
	v_and_b32_e32 v142, 0xffffffc0, v67
	v_and_b32_e32 v0, 7, v140
	v_subrev_u32_e32 v69, s14, v66
	v_mov_b64_e32 v[66:67], s[28:29]
	v_mov_b32_e32 v90, 0
	v_and_b32_e32 v141, 64, v140
	v_lshlrev_b32_e32 v0, 4, v0
	v_mad_i64_i32 v[132:133], s[8:9], v69, s19, v[66:67]
	v_mad_i64_i32 v[134:135], s[8:9], v68, s19, v[66:67]
	s_mov_b32 s14, -2
	v_mov_b32_e32 v91, v90
	v_mov_b32_e32 v92, v90
	v_mov_b32_e32 v93, v90
	v_mov_b32_e32 v66, v90
	v_mov_b32_e32 v67, v90
	v_mov_b32_e32 v68, v90
	v_mov_b32_e32 v69, v90
	v_mov_b32_e32 v74, v90
	v_mov_b32_e32 v75, v90
	v_mov_b32_e32 v76, v90
	v_mov_b32_e32 v77, v90
	v_mov_b32_e32 v86, v90
	v_mov_b32_e32 v87, v90
	v_mov_b32_e32 v88, v90
	v_mov_b32_e32 v89, v90
	v_mov_b32_e32 v70, v90
	v_mov_b32_e32 v71, v90
	v_mov_b32_e32 v72, v90
	v_mov_b32_e32 v73, v90
	v_mov_b32_e32 v78, v90
	v_mov_b32_e32 v79, v90
	v_mov_b32_e32 v80, v90
	v_mov_b32_e32 v81, v90
	v_mov_b32_e32 v82, v90
	v_mov_b32_e32 v83, v90
	v_mov_b32_e32 v84, v90
	v_mov_b32_e32 v85, v90
	v_mov_b32_e32 v94, v90
	v_mov_b32_e32 v95, v90
	v_mov_b32_e32 v96, v90
	v_mov_b32_e32 v97, v90
	v_mov_b32_e32 v98, v90
	v_mov_b32_e32 v99, v90
	v_mov_b32_e32 v100, v90
	v_mov_b32_e32 v101, v90
	v_mov_b32_e32 v102, v90
	v_mov_b32_e32 v103, v90
	v_mov_b32_e32 v104, v90
	v_mov_b32_e32 v105, v90
	v_mov_b32_e32 v106, v90
	v_mov_b32_e32 v107, v90
	v_mov_b32_e32 v108, v90
	v_mov_b32_e32 v109, v90
	v_mov_b32_e32 v110, v90
	v_mov_b32_e32 v111, v90
	v_mov_b32_e32 v112, v90
	v_mov_b32_e32 v113, v90
	v_mov_b32_e32 v118, v90
	v_mov_b32_e32 v119, v90
	v_mov_b32_e32 v120, v90
	v_mov_b32_e32 v121, v90
	v_mov_b32_e32 v122, v90
	v_mov_b32_e32 v123, v90
	v_mov_b32_e32 v124, v90
	v_mov_b32_e32 v125, v90
	v_mov_b32_e32 v126, v90
	v_mov_b32_e32 v127, v90
	v_mov_b32_e32 v128, v90
	v_mov_b32_e32 v129, v90
	v_mov_b32_e32 v114, v90
	v_mov_b32_e32 v115, v90
	v_mov_b32_e32 v116, v90
	v_mov_b32_e32 v117, v90
	s_branch .LBB0_1039
; DEV f32x4 mfma16(bf16x8 a, bf16x8 b, f32x4 c) { return __builtin_amdgcn_mfma_f32_16x16x32_bf16(a, b, c, 0, 0, 0); }
; #define G_LOAD(RA, RB, KT) { _Pragma("unroll") for (int i = 0; i < 4; i++) { \
;       RA[i] = *(const u32x4*)(Ap + (size_t)(i * 32) * lda + (KT) * 64); RB[i] = *(const u32x4*)(Bp + (size_t)(i * 32) * ldb + (KT) * 64); } }
; #define G_STORE(RA, RB) { _Pragma("unroll") for (int i = 0; i < 4; i++) { \
;       *(u32x4*)(As + (lrow + i * 32) * GLD + lcc * 8) = RA[i]; *(u32x4*)(Bs + (lrow + i * 32) * GLD + lcc * 8) = RB[i]; } }
; template <int TI, int TJ, int KS>
; DEV void mfma_lds(const bf16_t* Arows, int lda, const bf16_t* Brows, int ldb, int i0, int j0, f32x4 (&acc)[TI][TJ]) {
;     ...
;   for (int ks = 0; ks < KS; ks++) {
;     bf16x8 af[TI], bfr[TJ];
; #pragma unroll
;     for (int i = 0; i < TI; i++) af[i] = *(const bf16x8*)(Arows + (i0 + i * 16 + l15) * lda + ks * 32 + quad * 8);
; #pragma unroll
;     for (int j = 0; j < TJ; j++) bfr[j] = *(const bf16x8*)(Brows + (j0 + j * 16 + l15) * ldb + ks * 32 + quad * 8);
; #pragma unroll
;     for (int i = 0; i < TI; i++)
; #pragma unroll
;       for (int j = 0; j < TJ; j++) acc[i][j] = mfma16(af[i], bfr[j], acc[i][j]);
; template <class Epi>
; DEV void gemm_tile(const bf16_t* __restrict__ A, int lda, const bf16_t* __restrict__ Bt, int ldb, int K, int m0, int n0,
;                    Epi& epi, char* smem) {
;     ...
;   for (int kt = 0; kt < nk; kt += 2) {
;     __syncthreads();
;     G_STORE(ra0, rb0);
;     __syncthreads();
;     if (kt + 2 < nk) G_LOAD(ra0, rb0, kt + 2);
.LBB0_1038:
	v_mov_b32_e32 v131, v195
	v_and_b32_e32 v143, 15, v131
	v_or_b32_e32 v144, v143, v141
	v_and_b32_e32 v148, 48, v131
	v_mul_u32_u24_e32 v131, 0x50, v144
	v_lshl_add_u32 v131, v131, 1, v148
	v_or_b32_e32 v143, v143, v142
	v_mad_u32_u24 v238, v143, s36, v148
	v_lshl_add_u64 v[132:133], v[132:133], 0, s[34:35]
	v_lshl_add_u64 v[134:135], v[134:135], 0, s[34:35]
	s_and_b64 vcc, exec, s[8:9]
	ds_read_b128 v[148:151], v131 offset:20480
	ds_read_b128 v[164:167], v238
	ds_read_b128 v[168:171], v238 offset:2560
	ds_read_b128 v[172:175], v238 offset:5120
	ds_read_b128 v[176:179], v238 offset:7680
	ds_read_b128 v[152:155], v131 offset:23040
	ds_read_b128 v[156:159], v131 offset:25600
	ds_read_b128 v[160:163], v131 offset:28160
	ds_read_b128 v[180:183], v238 offset:64
	ds_read_b128 v[184:187], v238 offset:2624
	v_lshl_add_u64 v[188:189], v[188:189], 0, s[34:35]
	v_lshl_add_u64 v[190:191], v[190:191], 0, s[34:35]
	v_lshl_add_u64 v[192:193], v[192:193], 0, s[34:35]
	v_lshl_add_u64 v[236:237], v[236:237], 0, s[34:35]
	v_lshl_add_u64 v[240:241], v[240:241], 0, s[34:35]
	v_lshl_add_u64 v[242:243], v[242:243], 0, s[34:35]
	v_lshl_add_u64 v[244:245], v[244:245], 0, s[34:35]
	v_lshl_add_u64 v[246:247], v[246:247], 0, s[34:35]
	s_waitcnt lgkmcnt(8)
	v_mfma_f32_16x16x32_bf16 v[114:117], v[148:151], v[164:167], v[114:117]
	s_waitcnt lgkmcnt(7)
	v_mfma_f32_16x16x32_bf16 v[126:129], v[148:151], v[168:171], v[126:129]
	s_waitcnt lgkmcnt(6)
	v_mfma_f32_16x16x32_bf16 v[122:125], v[148:151], v[172:175], v[122:125]
	s_waitcnt lgkmcnt(5)
	v_mfma_f32_16x16x32_bf16 v[118:121], v[148:151], v[176:179], v[118:121]
	ds_read_b128 v[148:151], v131 offset:20544
	s_waitcnt lgkmcnt(5)
	v_mfma_f32_16x16x32_bf16 v[110:113], v[152:155], v[164:167], v[110:113]
	v_mfma_f32_16x16x32_bf16 v[106:109], v[152:155], v[168:171], v[106:109]
	v_mfma_f32_16x16x32_bf16 v[102:105], v[152:155], v[172:175], v[102:105]
	v_mfma_f32_16x16x32_bf16 v[98:101], v[152:155], v[176:179], v[98:101]
	ds_read_b128 v[152:155], v131 offset:23104
	s_waitcnt lgkmcnt(5)
	v_mfma_f32_16x16x32_bf16 v[94:97], v[156:159], v[164:167], v[94:97]
	v_mfma_f32_16x16x32_bf16 v[82:85], v[156:159], v[168:171], v[82:85]
	v_mfma_f32_16x16x32_bf16 v[78:81], v[156:159], v[172:175], v[78:81]
	v_mfma_f32_16x16x32_bf16 v[70:73], v[156:159], v[176:179], v[70:73]
	ds_read_b128 v[156:159], v131 offset:25664
	s_waitcnt lgkmcnt(5)
	v_mfma_f32_16x16x32_bf16 v[66:69], v[160:163], v[172:175], v[66:69]
	v_mfma_f32_16x16x32_bf16 v[90:93], v[160:163], v[176:179], v[90:93]
	ds_read_b128 v[172:175], v238 offset:5184
	ds_read_b128 v[176:179], v238 offset:7744
	v_mfma_f32_16x16x32_bf16 v[86:89], v[160:163], v[164:167], v[86:89]
	v_mfma_f32_16x16x32_bf16 v[74:77], v[160:163], v[168:171], v[74:77]
	ds_read_b128 v[160:163], v131 offset:28224
	s_waitcnt lgkmcnt(5)
	v_mfma_f32_16x16x32_bf16 v[114:117], v[148:151], v[180:183], v[114:117]
	s_waitcnt lgkmcnt(4)
	v_mfma_f32_16x16x32_bf16 v[110:113], v[152:155], v[180:183], v[110:113]
	s_waitcnt lgkmcnt(3)
	v_mfma_f32_16x16x32_bf16 v[94:97], v[156:159], v[180:183], v[94:97]
	v_mfma_f32_16x16x32_bf16 v[126:129], v[148:151], v[184:187], v[126:129]
	v_mfma_f32_16x16x32_bf16 v[106:109], v[152:155], v[184:187], v[106:109]
	v_mfma_f32_16x16x32_bf16 v[82:85], v[156:159], v[184:187], v[82:85]
	s_waitcnt lgkmcnt(2)
	v_mfma_f32_16x16x32_bf16 v[122:125], v[148:151], v[172:175], v[122:125]
	v_mfma_f32_16x16x32_bf16 v[102:105], v[152:155], v[172:175], v[102:105]
	v_mfma_f32_16x16x32_bf16 v[78:81], v[156:159], v[172:175], v[78:81]
	s_waitcnt lgkmcnt(1)
	v_mfma_f32_16x16x32_bf16 v[118:121], v[148:151], v[176:179], v[118:121]
	v_mfma_f32_16x16x32_bf16 v[98:101], v[152:155], v[176:179], v[98:101]
	v_mfma_f32_16x16x32_bf16 v[70:73], v[156:159], v[176:179], v[70:73]
	s_waitcnt lgkmcnt(0)
	v_mfma_f32_16x16x32_bf16 v[86:89], v[160:163], v[180:183], v[86:89]
	v_mfma_f32_16x16x32_bf16 v[74:77], v[160:163], v[184:187], v[74:77]
	v_mfma_f32_16x16x32_bf16 v[66:69], v[160:163], v[172:175], v[66:69]
	v_mfma_f32_16x16x32_bf16 v[90:93], v[160:163], v[176:179], v[90:93]
	s_cbranch_vccnz .LBB0_1043
.LBB0_1039:
	s_add_i32 s14, s14, 2
	s_cmp_gt_u32 s14, 13
	s_cselect_b64 s[8:9], -1, 0
	s_and_b64 vcc, exec, s[8:9]
	v_lshl_add_u64 v[138:139], v[134:135], 0, v[0:1]
	v_lshl_add_u64 v[136:137], v[132:133], 0, v[0:1]
	s_waitcnt lgkmcnt(0)
	s_barrier
	s_waitcnt vmcnt(8)
	ds_write_b128 v130, v[2:5]
	ds_write_b128 v130, v[10:13] offset:20480
	ds_write_b128 v130, v[18:21] offset:5120
	ds_write_b128 v130, v[26:29] offset:25600
	ds_write_b128 v130, v[34:37] offset:10240
	ds_write_b128 v130, v[42:45] offset:30720
	ds_write_b128 v130, v[50:53] offset:15360
	ds_write_b128 v130, v[58:61] offset:35840
	s_waitcnt lgkmcnt(0)
	s_barrier
	s_cbranch_vccnz .Lgw_skip_5
	global_load_dwordx4 v[2:5], v[188:189], off offset:256
	global_load_dwordx4 v[10:13], v[190:191], off offset:256
	global_load_dwordx4 v[18:21], v[192:193], off offset:256
	global_load_dwordx4 v[26:29], v[236:237], off offset:256
	global_load_dwordx4 v[34:37], v[240:241], off offset:256
	global_load_dwordx4 v[42:45], v[242:243], off offset:256
	global_load_dwordx4 v[50:53], v[244:245], off offset:256
	global_load_dwordx4 v[58:61], v[246:247], off offset:256
; DEV f32x4 mfma16(bf16x8 a, bf16x8 b, f32x4 c) { return __builtin_amdgcn_mfma_f32_16x16x32_bf16(a, b, c, 0, 0, 0); }
; #define G_LOAD(RA, RB, KT) { _Pragma("unroll") for (int i = 0; i < 4; i++) { \
;       RA[i] = *(const u32x4*)(Ap + (size_t)(i * 32) * lda + (KT) * 64); RB[i] = *(const u32x4*)(Bp + (size_t)(i * 32) * ldb + (KT) * 64); } }
; #define G_STORE(RA, RB) { _Pragma("unroll") for (int i = 0; i < 4; i++) { \
;       *(u32x4*)(As + (lrow + i * 32) * GLD + lcc * 8) = RA[i]; *(u32x4*)(Bs + (lrow + i * 32) * GLD + lcc * 8) = RB[i]; } }
; template <int TI, int TJ, int KS>
; DEV void mfma_lds(const bf16_t* Arows, int lda, const bf16_t* Brows, int ldb, int i0, int j0, f32x4 (&acc)[TI][TJ]) {
;     ...
;   for (int ks = 0; ks < KS; ks++) {
;     bf16x8 af[TI], bfr[TJ];
; #pragma unroll
;     for (int i = 0; i < TI; i++) af[i] = *(const bf16x8*)(Arows + (i0 + i * 16 + l15) * lda + ks * 32 + quad * 8);
; #pragma unroll
;     for (int j = 0; j < TJ; j++) bfr[j] = *(const bf16x8*)(Brows + (j0 + j * 16 + l15) * ldb + ks * 32 + quad * 8);
; #pragma unroll
;     for (int i = 0; i < TI; i++)
; #pragma unroll
;       for (int j = 0; j < TJ; j++) acc[i][j] = mfma16(af[i], bfr[j], acc[i][j]);
; template <class Epi>
; DEV void gemm_tile(const bf16_t* __restrict__ A, int lda, const bf16_t* __restrict__ Bt, int ldb, int K, int m0, int n0,
;                    Epi& epi, char* smem) {
;     ...
;     mfma_lds<4, 4, 2>(Bs, GLD, As, GLD, wn * 64, wm * 64, acc);
;     __syncthreads();
;     G_STORE(ra1, rb1);
;     __syncthreads();
;     if (kt + 3 < nk) G_LOAD(ra1, rb1, kt + 3);
.LBB0_1041:
	v_mov_b32_e32 v131, v195
	s_cmp_gt_u32 s14, 12
	v_and_b32_e32 v143, 15, v131
	v_or_b32_e32 v144, v143, v141
	v_and_b32_e32 v148, 48, v131
	v_mul_u32_u24_e32 v131, 0x50, v144
	v_lshl_add_u32 v131, v131, 1, v148
	v_or_b32_e32 v143, v143, v142
	v_mad_u32_u24 v238, v143, s36, v148
	ds_read_b128 v[148:151], v131 offset:20480
	ds_read_b128 v[164:167], v238
	ds_read_b128 v[168:171], v238 offset:2560
	ds_read_b128 v[172:175], v238 offset:5120
	ds_read_b128 v[176:179], v238 offset:7680
	ds_read_b128 v[152:155], v131 offset:23040
	ds_read_b128 v[156:159], v131 offset:25600
	ds_read_b128 v[160:163], v131 offset:28160
	ds_read_b128 v[180:183], v238 offset:64
	ds_read_b128 v[184:187], v238 offset:2624
	s_waitcnt lgkmcnt(8)
	v_mfma_f32_16x16x32_bf16 v[114:117], v[148:151], v[164:167], v[114:117]
	s_waitcnt lgkmcnt(7)
	v_mfma_f32_16x16x32_bf16 v[126:129], v[148:151], v[168:171], v[126:129]
	s_waitcnt lgkmcnt(6)
	v_mfma_f32_16x16x32_bf16 v[122:125], v[148:151], v[172:175], v[122:125]
	s_waitcnt lgkmcnt(5)
	v_mfma_f32_16x16x32_bf16 v[118:121], v[148:151], v[176:179], v[118:121]
	ds_read_b128 v[148:151], v131 offset:20544
	s_waitcnt lgkmcnt(5)
	v_mfma_f32_16x16x32_bf16 v[110:113], v[152:155], v[164:167], v[110:113]
	v_mfma_f32_16x16x32_bf16 v[106:109], v[152:155], v[168:171], v[106:109]
	v_mfma_f32_16x16x32_bf16 v[102:105], v[152:155], v[172:175], v[102:105]
	v_mfma_f32_16x16x32_bf16 v[98:101], v[152:155], v[176:179], v[98:101]
	ds_read_b128 v[152:155], v131 offset:23104
	s_waitcnt lgkmcnt(5)
	v_mfma_f32_16x16x32_bf16 v[94:97], v[156:159], v[164:167], v[94:97]
	v_mfma_f32_16x16x32_bf16 v[82:85], v[156:159], v[168:171], v[82:85]
	v_mfma_f32_16x16x32_bf16 v[78:81], v[156:159], v[172:175], v[78:81]
	v_mfma_f32_16x16x32_bf16 v[70:73], v[156:159], v[176:179], v[70:73]
	ds_read_b128 v[156:159], v131 offset:25664
	s_waitcnt lgkmcnt(5)
	v_mfma_f32_16x16x32_bf16 v[66:69], v[160:163], v[172:175], v[66:69]
	v_mfma_f32_16x16x32_bf16 v[90:93], v[160:163], v[176:179], v[90:93]
	ds_read_b128 v[172:175], v238 offset:5184
	ds_read_b128 v[176:179], v238 offset:7744
	v_mfma_f32_16x16x32_bf16 v[86:89], v[160:163], v[164:167], v[86:89]
	v_mfma_f32_16x16x32_bf16 v[74:77], v[160:163], v[168:171], v[74:77]
	ds_read_b128 v[160:163], v131 offset:28224
	s_waitcnt lgkmcnt(5)
	v_mfma_f32_16x16x32_bf16 v[114:117], v[148:151], v[180:183], v[114:117]
	s_waitcnt lgkmcnt(4)
	v_mfma_f32_16x16x32_bf16 v[110:113], v[152:155], v[180:183], v[110:113]
	s_waitcnt lgkmcnt(3)
	v_mfma_f32_16x16x32_bf16 v[94:97], v[156:159], v[180:183], v[94:97]
	v_mfma_f32_16x16x32_bf16 v[126:129], v[148:151], v[184:187], v[126:129]
	v_mfma_f32_16x16x32_bf16 v[106:109], v[152:155], v[184:187], v[106:109]
	v_mfma_f32_16x16x32_bf16 v[82:85], v[156:159], v[184:187], v[82:85]
	s_waitcnt lgkmcnt(2)
	v_mfma_f32_16x16x32_bf16 v[122:125], v[148:151], v[172:175], v[122:125]
	v_mfma_f32_16x16x32_bf16 v[102:105], v[152:155], v[172:175], v[102:105]
	v_mfma_f32_16x16x32_bf16 v[78:81], v[156:159], v[172:175], v[78:81]
	s_waitcnt lgkmcnt(1)
	v_mfma_f32_16x16x32_bf16 v[118:121], v[148:151], v[176:179], v[118:121]
	v_mfma_f32_16x16x32_bf16 v[98:101], v[152:155], v[176:179], v[98:101]
	v_mfma_f32_16x16x32_bf16 v[70:73], v[156:159], v[176:179], v[70:73]
	s_waitcnt lgkmcnt(0)
	v_mfma_f32_16x16x32_bf16 v[86:89], v[160:163], v[180:183], v[86:89]
	s_barrier
	v_mfma_f32_16x16x32_bf16 v[74:77], v[160:163], v[184:187], v[74:77]
	s_waitcnt vmcnt(8)
	ds_write_b128 v130, v[6:9]
	ds_write_b128 v130, v[14:17] offset:20480
	ds_write_b128 v130, v[22:25] offset:5120
	ds_write_b128 v130, v[30:33] offset:25600
	ds_write_b128 v130, v[38:41] offset:10240
	ds_write_b128 v130, v[46:49] offset:30720
	ds_write_b128 v130, v[54:57] offset:15360
	ds_write_b128 v130, v[62:65] offset:35840
	v_mfma_f32_16x16x32_bf16 v[66:69], v[160:163], v[172:175], v[66:69]
	s_waitcnt lgkmcnt(0)
	s_barrier
	v_mfma_f32_16x16x32_bf16 v[90:93], v[160:163], v[176:179], v[90:93]
	s_cbranch_scc1 .LBB0_1038
	global_load_dwordx4 v[6:9], v[188:189], off offset:384
	global_load_dwordx4 v[14:17], v[190:191], off offset:384
	global_load_dwordx4 v[22:25], v[192:193], off offset:384
	global_load_dwordx4 v[30:33], v[236:237], off offset:384
	global_load_dwordx4 v[38:41], v[240:241], off offset:384
	global_load_dwordx4 v[46:49], v[242:243], off offset:384
	global_load_dwordx4 v[54:57], v[244:245], off offset:384
	global_load_dwordx4 v[62:65], v[246:247], off offset:384
	s_branch .LBB0_1038
